# v38 + GEMM K-loops: redundant lgkmcnt(0) after barrier and mid-phase setprio 0/1 pairs deleted (32+32 sites)
# speedup vs baseline: 1.0148x; 1.0148x over previous
.LBB0_248:
	s_add_u32 s6, s54, 0xfffc0080
	s_addc_u32 s20, s55, -1
	s_add_i32 s21, 0, 0x10000
	s_cmp_eq_u32 s68, 12
	s_cselect_b32 s59, s33, s20
	s_cselect_b32 s58, s39, s6
	v_add_u32_e32 v48, s21, v173
	s_cselect_b32 s57, s45, s67
	s_cselect_b32 s56, s47, s66
	s_add_i32 s6, 0, 0x14000
	ds_read_b128 v[138:141], v48
	ds_read_b128 v[142:145], v48 offset:1024
	ds_read_b128 v[146:149], v48 offset:2048
	ds_read_b128 v[150:153], v48 offset:3072
	v_add_u32_e32 v48, s6, v173
	ds_read_b128 v[156:159], v48
	ds_read_b128 v[160:163], v48 offset:1024
	ds_read_b128 v[164:167], v48 offset:2048
	ds_read_b128 v[168:171], v48 offset:3072
	v_lshl_add_u64 v[202:203], s[54:55], 0, v[134:135]
	s_add_i32 m0, s60, 0xc000
	ds_read_b128 v[178:181], v176
	ds_read_b128 v[182:185], v176 offset:1024
	ds_read_b128 v[186:189], v176 offset:2048
	ds_read_b128 v[190:193], v176 offset:3072
	ds_read_b128 v[194:197], v176 offset:4096
	ds_read_b128 v[198:201], v176 offset:5120
	ds_read_b128 v[216:219], v176 offset:6144
	ds_read_b128 v[220:223], v176 offset:7168
	global_load_lds_dwordx4 v[202:203], off
	v_lshl_add_u64 v[202:203], s[54:55], 0, v[136:137]
	s_add_i32 m0, s60, 0xe000
	s_nop 0
	global_load_lds_dwordx4 v[202:203], off
	s_waitcnt vmcnt(8)
	s_waitcnt lgkmcnt(0)
	s_barrier
	s_setprio 1
	v_mfma_f32_16x16x32_bf16 v[126:129], v[138:141], v[178:181], v[126:129]
	v_mfma_f32_16x16x32_bf16 v[122:125], v[146:149], v[178:181], v[122:125]
	v_mfma_f32_16x16x32_bf16 v[110:113], v[138:141], v[186:189], v[110:113]
	v_mfma_f32_16x16x32_bf16 v[106:109], v[146:149], v[186:189], v[106:109]
	v_mfma_f32_16x16x32_bf16 v[94:97], v[138:141], v[194:197], v[94:97]
	v_mfma_f32_16x16x32_bf16 v[90:93], v[146:149], v[194:197], v[90:93]
	v_mfma_f32_16x16x32_bf16 v[78:81], v[138:141], v[216:219], v[78:81]
	v_mfma_f32_16x16x32_bf16 v[74:77], v[146:149], v[216:219], v[74:77]
	v_mfma_f32_16x16x32_bf16 v[126:129], v[142:145], v[182:185], v[126:129]
	v_mfma_f32_16x16x32_bf16 v[122:125], v[150:153], v[182:185], v[122:125]
	v_mfma_f32_16x16x32_bf16 v[110:113], v[142:145], v[190:193], v[110:113]
	v_mfma_f32_16x16x32_bf16 v[106:109], v[150:153], v[190:193], v[106:109]
	v_mfma_f32_16x16x32_bf16 v[94:97], v[142:145], v[198:201], v[94:97]
	v_mfma_f32_16x16x32_bf16 v[90:93], v[150:153], v[198:201], v[90:93]
	v_mfma_f32_16x16x32_bf16 v[78:81], v[142:145], v[220:223], v[78:81]
	v_mfma_f32_16x16x32_bf16 v[74:77], v[150:153], v[220:223], v[74:77]
	v_mfma_f32_16x16x32_bf16 v[118:121], v[156:159], v[178:181], v[118:121]
	v_mfma_f32_16x16x32_bf16 v[114:117], v[164:167], v[178:181], v[114:117]
	v_mfma_f32_16x16x32_bf16 v[102:105], v[156:159], v[186:189], v[102:105]
	v_mfma_f32_16x16x32_bf16 v[98:101], v[164:167], v[186:189], v[98:101]
	v_mfma_f32_16x16x32_bf16 v[86:89], v[156:159], v[194:197], v[86:89]
	v_mfma_f32_16x16x32_bf16 v[82:85], v[164:167], v[194:197], v[82:85]
	v_mfma_f32_16x16x32_bf16 v[70:73], v[156:159], v[216:219], v[70:73]
	v_mfma_f32_16x16x32_bf16 v[66:69], v[164:167], v[216:219], v[66:69]
	v_mfma_f32_16x16x32_bf16 v[118:121], v[160:163], v[182:185], v[118:121]
	v_mfma_f32_16x16x32_bf16 v[114:117], v[168:171], v[182:185], v[114:117]
	v_mfma_f32_16x16x32_bf16 v[102:105], v[160:163], v[190:193], v[102:105]
	v_mfma_f32_16x16x32_bf16 v[98:101], v[168:171], v[190:193], v[98:101]
	v_mfma_f32_16x16x32_bf16 v[86:89], v[160:163], v[198:201], v[86:89]
	v_mfma_f32_16x16x32_bf16 v[82:85], v[168:171], v[198:201], v[82:85]
	v_mfma_f32_16x16x32_bf16 v[70:73], v[160:163], v[220:223], v[70:73]
	v_mfma_f32_16x16x32_bf16 v[66:69], v[168:171], v[220:223], v[66:69]
	s_setprio 0
	s_barrier
	s_add_i32 s20, s21, s9
	v_lshl_add_u64 v[202:203], s[56:57], 0, v[132:133]
	s_mov_b32 m0, s20
	ds_read_b128 v[178:181], v176 offset:16384
	ds_read_b128 v[182:185], v176 offset:17408
	ds_read_b128 v[186:189], v176 offset:18432
	ds_read_b128 v[190:193], v176 offset:19456
	ds_read_b128 v[194:197], v176 offset:20480
	ds_read_b128 v[198:201], v176 offset:21504
	ds_read_b128 v[216:219], v176 offset:22528
	ds_read_b128 v[220:223], v176 offset:23552
	global_load_lds_dwordx4 v[202:203], off
	s_add_i32 m0, s20, 0x2000
	s_add_u32 s20, s56, 0x40000
	v_lshl_add_u64 v[224:225], s[56:57], 0, v[130:131]
	s_addc_u32 s21, s57, 0
	s_add_i32 s6, s6, s9
	global_load_lds_dwordx4 v[224:225], off
	v_lshl_add_u64 v[226:227], s[20:21], 0, v[132:133]
	s_mov_b32 m0, s6
	v_lshl_add_u64 v[228:229], s[58:59], 0, v[130:131]
	global_load_lds_dwordx4 v[226:227], off
	v_lshl_add_u64 v[226:227], s[20:21], 0, v[130:131]
	s_add_i32 m0, s6, 0x2000
	s_nop 0
	global_load_lds_dwordx4 v[226:227], off
	v_lshl_add_u64 v[226:227], s[58:59], 0, v[132:133]
	s_mov_b32 m0, s60
	s_nop 0
	global_load_lds_dwordx4 v[226:227], off
	s_mov_b32 m0, s61
	s_nop 0
	global_load_lds_dwordx4 v[228:229], off
	s_waitcnt vmcnt(8)
	s_waitcnt lgkmcnt(0)
	s_barrier
	s_setprio 1
	v_mfma_f32_16x16x32_bf16 v[62:65], v[138:141], v[178:181], v[62:65]
	v_mfma_f32_16x16x32_bf16 v[58:61], v[146:149], v[178:181], v[58:61]
	v_mfma_f32_16x16x32_bf16 v[44:47], v[138:141], v[186:189], v[44:47]
	v_mfma_f32_16x16x32_bf16 v[40:43], v[146:149], v[186:189], v[40:43]
	v_mfma_f32_16x16x32_bf16 v[28:31], v[138:141], v[194:197], v[28:31]
	v_mfma_f32_16x16x32_bf16 v[24:27], v[146:149], v[194:197], v[24:27]
	v_mfma_f32_16x16x32_bf16 v[12:15], v[138:141], v[216:219], v[12:15]
	v_mfma_f32_16x16x32_bf16 v[8:11], v[146:149], v[216:219], v[8:11]
	v_mfma_f32_16x16x32_bf16 v[62:65], v[142:145], v[182:185], v[62:65]
	v_mfma_f32_16x16x32_bf16 v[58:61], v[150:153], v[182:185], v[58:61]
	v_mfma_f32_16x16x32_bf16 v[44:47], v[142:145], v[190:193], v[44:47]
	v_mfma_f32_16x16x32_bf16 v[40:43], v[150:153], v[190:193], v[40:43]
	v_mfma_f32_16x16x32_bf16 v[28:31], v[142:145], v[198:201], v[28:31]
	v_mfma_f32_16x16x32_bf16 v[24:27], v[150:153], v[198:201], v[24:27]
	v_mfma_f32_16x16x32_bf16 v[12:15], v[142:145], v[220:223], v[12:15]
	v_mfma_f32_16x16x32_bf16 v[8:11], v[150:153], v[220:223], v[8:11]
	v_mfma_f32_16x16x32_bf16 v[54:57], v[156:159], v[178:181], v[54:57]
	v_mfma_f32_16x16x32_bf16 v[50:53], v[164:167], v[178:181], v[50:53]
	v_mfma_f32_16x16x32_bf16 v[36:39], v[156:159], v[186:189], v[36:39]
	v_mfma_f32_16x16x32_bf16 v[32:35], v[164:167], v[186:189], v[32:35]
	v_mfma_f32_16x16x32_bf16 v[20:23], v[156:159], v[194:197], v[20:23]
	v_mfma_f32_16x16x32_bf16 v[16:19], v[164:167], v[194:197], v[16:19]
	v_mfma_f32_16x16x32_bf16 v[4:7], v[156:159], v[216:219], v[4:7]
	v_mfma_f32_16x16x32_bf16 v[0:3], v[164:167], v[216:219], v[0:3]
	v_mfma_f32_16x16x32_bf16 v[54:57], v[160:163], v[182:185], v[54:57]
	v_mfma_f32_16x16x32_bf16 v[50:53], v[168:171], v[182:185], v[50:53]
	v_mfma_f32_16x16x32_bf16 v[36:39], v[160:163], v[190:193], v[36:39]
	v_mfma_f32_16x16x32_bf16 v[32:35], v[168:171], v[190:193], v[32:35]
	v_mfma_f32_16x16x32_bf16 v[20:23], v[160:163], v[198:201], v[20:23]
	v_mfma_f32_16x16x32_bf16 v[16:19], v[168:171], v[198:201], v[16:19]
	v_mfma_f32_16x16x32_bf16 v[4:7], v[160:163], v[220:223], v[4:7]
	v_mfma_f32_16x16x32_bf16 v[0:3], v[168:171], v[220:223], v[0:3]
	s_setprio 0
	s_barrier
	s_add_i32 s6, 0, 0x18000
	v_add_u32_e32 v48, s6, v173
	s_add_i32 s26, 0, 0x1c000
	ds_read_b128 v[138:141], v48
	ds_read_b128 v[142:145], v48 offset:1024
	ds_read_b128 v[146:149], v48 offset:2048
	ds_read_b128 v[150:153], v48 offset:3072
	v_add_u32_e32 v48, s26, v173
	ds_read_b128 v[156:159], v48
	ds_read_b128 v[160:163], v48 offset:1024
	ds_read_b128 v[164:167], v48 offset:2048
	ds_read_b128 v[168:171], v48 offset:3072
	s_add_u32 s20, s58, 0x40000
	s_addc_u32 s21, s59, 0
	s_mov_b32 m0, s62
	v_lshl_add_u64 v[230:231], s[20:21], 0, v[132:133]
	ds_read_b128 v[178:181], v176 offset:32768
	ds_read_b128 v[182:185], v176 offset:33792
	ds_read_b128 v[186:189], v176 offset:34816
	ds_read_b128 v[190:193], v176 offset:35840
	ds_read_b128 v[194:197], v176 offset:36864
	ds_read_b128 v[198:201], v176 offset:37888
	ds_read_b128 v[216:219], v176 offset:38912
	ds_read_b128 v[220:223], v176 offset:39936
	global_load_lds_dwordx4 v[230:231], off
	v_lshl_add_u64 v[230:231], s[20:21], 0, v[130:131]
	s_mov_b32 m0, s63
	s_nop 0
	global_load_lds_dwordx4 v[230:231], off
	s_waitcnt vmcnt(8)
	s_waitcnt lgkmcnt(0)
	s_barrier
	s_setprio 1
	v_mfma_f32_16x16x32_bf16 v[126:129], v[138:141], v[178:181], v[126:129]
	v_mfma_f32_16x16x32_bf16 v[122:125], v[146:149], v[178:181], v[122:125]
	v_mfma_f32_16x16x32_bf16 v[110:113], v[138:141], v[186:189], v[110:113]
	v_mfma_f32_16x16x32_bf16 v[106:109], v[146:149], v[186:189], v[106:109]
	v_mfma_f32_16x16x32_bf16 v[94:97], v[138:141], v[194:197], v[94:97]
	v_mfma_f32_16x16x32_bf16 v[90:93], v[146:149], v[194:197], v[90:93]
	v_mfma_f32_16x16x32_bf16 v[78:81], v[138:141], v[216:219], v[78:81]
	v_mfma_f32_16x16x32_bf16 v[74:77], v[146:149], v[216:219], v[74:77]
	v_mfma_f32_16x16x32_bf16 v[126:129], v[142:145], v[182:185], v[126:129]
	v_mfma_f32_16x16x32_bf16 v[122:125], v[150:153], v[182:185], v[122:125]
	v_mfma_f32_16x16x32_bf16 v[110:113], v[142:145], v[190:193], v[110:113]
	v_mfma_f32_16x16x32_bf16 v[106:109], v[150:153], v[190:193], v[106:109]
	v_mfma_f32_16x16x32_bf16 v[94:97], v[142:145], v[198:201], v[94:97]
	v_mfma_f32_16x16x32_bf16 v[90:93], v[150:153], v[198:201], v[90:93]
	v_mfma_f32_16x16x32_bf16 v[78:81], v[142:145], v[220:223], v[78:81]
	v_mfma_f32_16x16x32_bf16 v[74:77], v[150:153], v[220:223], v[74:77]
	v_mfma_f32_16x16x32_bf16 v[118:121], v[156:159], v[178:181], v[118:121]
	v_mfma_f32_16x16x32_bf16 v[114:117], v[164:167], v[178:181], v[114:117]
	v_mfma_f32_16x16x32_bf16 v[102:105], v[156:159], v[186:189], v[102:105]
	v_mfma_f32_16x16x32_bf16 v[98:101], v[164:167], v[186:189], v[98:101]
	v_mfma_f32_16x16x32_bf16 v[86:89], v[156:159], v[194:197], v[86:89]
	v_mfma_f32_16x16x32_bf16 v[82:85], v[164:167], v[194:197], v[82:85]
	v_mfma_f32_16x16x32_bf16 v[70:73], v[156:159], v[216:219], v[70:73]
	v_mfma_f32_16x16x32_bf16 v[66:69], v[164:167], v[216:219], v[66:69]
	v_mfma_f32_16x16x32_bf16 v[118:121], v[160:163], v[182:185], v[118:121]
	v_mfma_f32_16x16x32_bf16 v[114:117], v[168:171], v[182:185], v[114:117]
	v_mfma_f32_16x16x32_bf16 v[102:105], v[160:163], v[190:193], v[102:105]
	v_mfma_f32_16x16x32_bf16 v[98:101], v[168:171], v[190:193], v[98:101]
	v_mfma_f32_16x16x32_bf16 v[86:89], v[160:163], v[198:201], v[86:89]
	v_mfma_f32_16x16x32_bf16 v[82:85], v[168:171], v[198:201], v[82:85]
	v_mfma_f32_16x16x32_bf16 v[70:73], v[160:163], v[220:223], v[70:73]
	v_mfma_f32_16x16x32_bf16 v[66:69], v[168:171], v[220:223], v[66:69]
	s_setprio 0
	s_barrier
	s_add_i32 s6, s6, s9
	v_lshl_add_u64 v[202:203], v[202:203], 0, s[30:31]
	s_mov_b32 m0, s6
	ds_read_b128 v[178:181], v176 offset:49152
	ds_read_b128 v[182:185], v176 offset:50176
	ds_read_b128 v[186:189], v176 offset:51200
	ds_read_b128 v[190:193], v176 offset:52224
	ds_read_b128 v[194:197], v176 offset:53248
	ds_read_b128 v[198:201], v176 offset:54272
	ds_read_b128 v[216:219], v176 offset:55296
	ds_read_b128 v[220:223], v176 offset:56320
	global_load_lds_dwordx4 v[202:203], off
	s_add_i32 m0, s6, 0x2000
	s_add_u32 s20, s56, 0x40080
	v_lshl_add_u64 v[202:203], v[224:225], 0, s[30:31]
	s_addc_u32 s21, s57, 0
	s_add_i32 s6, s26, s9
	global_load_lds_dwordx4 v[202:203], off
	v_lshl_add_u64 v[202:203], s[20:21], 0, v[132:133]
	s_mov_b32 m0, s6
	s_nop 0
	global_load_lds_dwordx4 v[202:203], off
	v_lshl_add_u64 v[202:203], s[20:21], 0, v[130:131]
	s_add_i32 m0, s6, 0x2000
	s_nop 0
	global_load_lds_dwordx4 v[202:203], off
	v_lshl_add_u64 v[202:203], v[226:227], 0, s[30:31]
	s_mov_b32 m0, s64
	s_nop 0
	global_load_lds_dwordx4 v[202:203], off
	v_lshl_add_u64 v[202:203], v[228:229], 0, s[30:31]
	s_mov_b32 m0, s65
	s_nop 0
	global_load_lds_dwordx4 v[202:203], off
	s_waitcnt vmcnt(8)
	s_waitcnt lgkmcnt(0)
	s_barrier
	s_setprio 1
	v_mfma_f32_16x16x32_bf16 v[62:65], v[138:141], v[178:181], v[62:65]
	v_mfma_f32_16x16x32_bf16 v[58:61], v[146:149], v[178:181], v[58:61]
	v_mfma_f32_16x16x32_bf16 v[44:47], v[138:141], v[186:189], v[44:47]
	v_mfma_f32_16x16x32_bf16 v[40:43], v[146:149], v[186:189], v[40:43]
	v_mfma_f32_16x16x32_bf16 v[28:31], v[138:141], v[194:197], v[28:31]
	v_mfma_f32_16x16x32_bf16 v[24:27], v[146:149], v[194:197], v[24:27]
	v_mfma_f32_16x16x32_bf16 v[12:15], v[138:141], v[216:219], v[12:15]
	v_mfma_f32_16x16x32_bf16 v[8:11], v[146:149], v[216:219], v[8:11]
	v_mfma_f32_16x16x32_bf16 v[62:65], v[142:145], v[182:185], v[62:65]
	v_mfma_f32_16x16x32_bf16 v[58:61], v[150:153], v[182:185], v[58:61]
	v_mfma_f32_16x16x32_bf16 v[44:47], v[142:145], v[190:193], v[44:47]
	v_mfma_f32_16x16x32_bf16 v[40:43], v[150:153], v[190:193], v[40:43]
	v_mfma_f32_16x16x32_bf16 v[28:31], v[142:145], v[198:201], v[28:31]
	v_mfma_f32_16x16x32_bf16 v[24:27], v[150:153], v[198:201], v[24:27]
	v_mfma_f32_16x16x32_bf16 v[12:15], v[142:145], v[220:223], v[12:15]
	v_mfma_f32_16x16x32_bf16 v[8:11], v[150:153], v[220:223], v[8:11]
	v_mfma_f32_16x16x32_bf16 v[54:57], v[156:159], v[178:181], v[54:57]
	v_mfma_f32_16x16x32_bf16 v[50:53], v[164:167], v[178:181], v[50:53]
	v_mfma_f32_16x16x32_bf16 v[36:39], v[156:159], v[186:189], v[36:39]
	v_mfma_f32_16x16x32_bf16 v[32:35], v[164:167], v[186:189], v[32:35]
	v_mfma_f32_16x16x32_bf16 v[20:23], v[156:159], v[194:197], v[20:23]
	v_mfma_f32_16x16x32_bf16 v[16:19], v[164:167], v[194:197], v[16:19]
	v_mfma_f32_16x16x32_bf16 v[4:7], v[156:159], v[216:219], v[4:7]
	v_mfma_f32_16x16x32_bf16 v[0:3], v[164:167], v[216:219], v[0:3]
	v_mfma_f32_16x16x32_bf16 v[54:57], v[160:163], v[182:185], v[54:57]
	v_mfma_f32_16x16x32_bf16 v[50:53], v[168:171], v[182:185], v[50:53]
	v_mfma_f32_16x16x32_bf16 v[36:39], v[160:163], v[190:193], v[36:39]
	v_mfma_f32_16x16x32_bf16 v[32:35], v[168:171], v[190:193], v[32:35]
	v_mfma_f32_16x16x32_bf16 v[20:23], v[160:163], v[198:201], v[20:23]
	v_mfma_f32_16x16x32_bf16 v[16:19], v[168:171], v[198:201], v[16:19]
	v_mfma_f32_16x16x32_bf16 v[4:7], v[160:163], v[220:223], v[4:7]
	v_mfma_f32_16x16x32_bf16 v[0:3], v[168:171], v[220:223], v[0:3]
	s_setprio 0
	s_barrier
	s_add_i32 s68, s68, 2
	s_add_u32 s54, s54, 0x100
	s_addc_u32 s55, s55, 0
	s_add_u32 s66, s66, 0x100
	s_addc_u32 s67, s67, 0
	s_cmp_gt_u32 s68, 13
	s_cbranch_scc0 .LBB0_248
	s_and_b64 vcc, exec, s[42:43]
	s_cbranch_vccz .LBB0_251
	s_barrier

.LBB0_472:
	s_add_u32 s52, s50, 0x100
	s_addc_u32 s53, s51, 0
	s_add_i32 s6, 0, 0x10000
	s_cmp_eq_u32 s71, 40
	s_cselect_b32 s57, s47, s53
	s_cselect_b32 s56, s46, s52
	v_add_u32_e32 v48, s6, v183
	s_cselect_b32 s55, s49, s70
	s_cselect_b32 s54, s48, s69
	s_add_i32 s26, 0, 0x14000
	ds_read_b128 v[122:125], v48
	ds_read_b128 v[130:133], v48 offset:1024
	ds_read_b128 v[138:141], v48 offset:2048
	ds_read_b128 v[142:145], v48 offset:3072
	v_add_u32_e32 v48, s26, v183
	ds_read_b128 v[146:149], v48
	ds_read_b128 v[150:153], v48 offset:1024
	ds_read_b128 v[168:171], v48 offset:2048
	ds_read_b128 v[172:175], v48 offset:3072
	v_lshl_add_u64 v[180:181], s[50:51], 0, v[164:165]
	s_add_i32 m0, s59, 0xc000
	ds_read_b128 v[176:179], v185
	ds_read_b128 v[186:189], v185 offset:1024
	ds_read_b128 v[190:193], v185 offset:2048
	ds_read_b128 v[194:197], v185 offset:3072
	ds_read_b128 v[198:201], v185 offset:4096
	ds_read_b128 v[216:219], v185 offset:5120
	ds_read_b128 v[220:223], v185 offset:6144
	ds_read_b128 v[224:227], v185 offset:7168
	global_load_lds_dwordx4 v[180:181], off
	v_lshl_add_u64 v[180:181], s[50:51], 0, v[166:167]
	s_add_i32 m0, s59, 0xe000
	s_nop 0
	global_load_lds_dwordx4 v[180:181], off
	s_waitcnt vmcnt(8)
	s_waitcnt lgkmcnt(0)
	s_barrier
	s_setprio 1
	v_mfma_f32_16x16x32_bf16 v[134:137], v[122:125], v[176:179], v[134:137]
	v_mfma_f32_16x16x32_bf16 v[126:129], v[138:141], v[176:179], v[126:129]
	v_mfma_f32_16x16x32_bf16 v[110:113], v[122:125], v[190:193], v[110:113]
	v_mfma_f32_16x16x32_bf16 v[106:109], v[138:141], v[190:193], v[106:109]
	v_mfma_f32_16x16x32_bf16 v[94:97], v[122:125], v[198:201], v[94:97]
	v_mfma_f32_16x16x32_bf16 v[90:93], v[138:141], v[198:201], v[90:93]
	v_mfma_f32_16x16x32_bf16 v[78:81], v[122:125], v[220:223], v[78:81]
	v_mfma_f32_16x16x32_bf16 v[74:77], v[138:141], v[220:223], v[74:77]
	v_mfma_f32_16x16x32_bf16 v[134:137], v[130:133], v[186:189], v[134:137]
	v_mfma_f32_16x16x32_bf16 v[126:129], v[142:145], v[186:189], v[126:129]
	v_mfma_f32_16x16x32_bf16 v[110:113], v[130:133], v[194:197], v[110:113]
	v_mfma_f32_16x16x32_bf16 v[106:109], v[142:145], v[194:197], v[106:109]
	v_mfma_f32_16x16x32_bf16 v[94:97], v[130:133], v[216:219], v[94:97]
	v_mfma_f32_16x16x32_bf16 v[90:93], v[142:145], v[216:219], v[90:93]
	v_mfma_f32_16x16x32_bf16 v[78:81], v[130:133], v[224:227], v[78:81]
	v_mfma_f32_16x16x32_bf16 v[74:77], v[142:145], v[224:227], v[74:77]
	v_mfma_f32_16x16x32_bf16 v[118:121], v[146:149], v[176:179], v[118:121]
	v_mfma_f32_16x16x32_bf16 v[114:117], v[168:171], v[176:179], v[114:117]
	v_mfma_f32_16x16x32_bf16 v[102:105], v[146:149], v[190:193], v[102:105]
	v_mfma_f32_16x16x32_bf16 v[98:101], v[168:171], v[190:193], v[98:101]
	v_mfma_f32_16x16x32_bf16 v[86:89], v[146:149], v[198:201], v[86:89]
	v_mfma_f32_16x16x32_bf16 v[82:85], v[168:171], v[198:201], v[82:85]
	v_mfma_f32_16x16x32_bf16 v[70:73], v[146:149], v[220:223], v[70:73]
	v_mfma_f32_16x16x32_bf16 v[66:69], v[168:171], v[220:223], v[66:69]
	v_mfma_f32_16x16x32_bf16 v[118:121], v[150:153], v[186:189], v[118:121]
	v_mfma_f32_16x16x32_bf16 v[114:117], v[172:175], v[186:189], v[114:117]
	v_mfma_f32_16x16x32_bf16 v[102:105], v[150:153], v[194:197], v[102:105]
	v_mfma_f32_16x16x32_bf16 v[98:101], v[172:175], v[194:197], v[98:101]
	v_mfma_f32_16x16x32_bf16 v[86:89], v[150:153], v[216:219], v[86:89]
	v_mfma_f32_16x16x32_bf16 v[82:85], v[172:175], v[216:219], v[82:85]
	v_mfma_f32_16x16x32_bf16 v[70:73], v[150:153], v[224:227], v[70:73]
	v_mfma_f32_16x16x32_bf16 v[66:69], v[172:175], v[224:227], v[66:69]
	s_setprio 0
	s_barrier
	s_add_i32 s6, s6, s58
	v_lshl_add_u64 v[180:181], s[54:55], 0, v[158:159]
	s_mov_b32 m0, s6
	ds_read_b128 v[176:179], v185 offset:16384
	ds_read_b128 v[186:189], v185 offset:17408
	ds_read_b128 v[190:193], v185 offset:18432
	ds_read_b128 v[194:197], v185 offset:19456
	ds_read_b128 v[198:201], v185 offset:20480
	ds_read_b128 v[216:219], v185 offset:21504
	ds_read_b128 v[220:223], v185 offset:22528
	ds_read_b128 v[224:227], v185 offset:23552
	global_load_lds_dwordx4 v[180:181], off
	s_add_i32 m0, s6, 0x2000
	s_add_u32 s20, s54, 0xb0000
	v_lshl_add_u64 v[202:203], s[54:55], 0, v[162:163]
	s_addc_u32 s21, s55, 0
	s_add_i32 s6, s26, s58
	global_load_lds_dwordx4 v[202:203], off
	v_lshl_add_u64 v[228:229], s[20:21], 0, v[158:159]
	s_mov_b32 m0, s6
	v_lshl_add_u64 v[230:231], s[56:57], 0, v[160:161]
	global_load_lds_dwordx4 v[228:229], off
	v_lshl_add_u64 v[228:229], s[20:21], 0, v[162:163]
	s_add_i32 m0, s6, 0x2000
	s_nop 0
	global_load_lds_dwordx4 v[228:229], off
	v_lshl_add_u64 v[228:229], s[56:57], 0, v[156:157]
	s_mov_b32 m0, s59
	s_nop 0
	global_load_lds_dwordx4 v[228:229], off
	s_mov_b32 m0, s60
	s_nop 0
	global_load_lds_dwordx4 v[230:231], off
	s_waitcnt vmcnt(8)
	s_waitcnt lgkmcnt(0)
	s_barrier
	s_setprio 1
	v_mfma_f32_16x16x32_bf16 v[62:65], v[122:125], v[176:179], v[62:65]
	v_mfma_f32_16x16x32_bf16 v[58:61], v[138:141], v[176:179], v[58:61]
	v_mfma_f32_16x16x32_bf16 v[44:47], v[122:125], v[190:193], v[44:47]
	v_mfma_f32_16x16x32_bf16 v[40:43], v[138:141], v[190:193], v[40:43]
	v_mfma_f32_16x16x32_bf16 v[28:31], v[122:125], v[198:201], v[28:31]
	v_mfma_f32_16x16x32_bf16 v[24:27], v[138:141], v[198:201], v[24:27]
	v_mfma_f32_16x16x32_bf16 v[12:15], v[122:125], v[220:223], v[12:15]
	v_mfma_f32_16x16x32_bf16 v[8:11], v[138:141], v[220:223], v[8:11]
	v_mfma_f32_16x16x32_bf16 v[62:65], v[130:133], v[186:189], v[62:65]
	v_mfma_f32_16x16x32_bf16 v[58:61], v[142:145], v[186:189], v[58:61]
	v_mfma_f32_16x16x32_bf16 v[44:47], v[130:133], v[194:197], v[44:47]
	v_mfma_f32_16x16x32_bf16 v[40:43], v[142:145], v[194:197], v[40:43]
	v_mfma_f32_16x16x32_bf16 v[28:31], v[130:133], v[216:219], v[28:31]
	v_mfma_f32_16x16x32_bf16 v[24:27], v[142:145], v[216:219], v[24:27]
	v_mfma_f32_16x16x32_bf16 v[12:15], v[130:133], v[224:227], v[12:15]
	v_mfma_f32_16x16x32_bf16 v[8:11], v[142:145], v[224:227], v[8:11]
	v_mfma_f32_16x16x32_bf16 v[54:57], v[146:149], v[176:179], v[54:57]
	v_mfma_f32_16x16x32_bf16 v[50:53], v[168:171], v[176:179], v[50:53]
	v_mfma_f32_16x16x32_bf16 v[36:39], v[146:149], v[190:193], v[36:39]
	v_mfma_f32_16x16x32_bf16 v[32:35], v[168:171], v[190:193], v[32:35]
	v_mfma_f32_16x16x32_bf16 v[20:23], v[146:149], v[198:201], v[20:23]
	v_mfma_f32_16x16x32_bf16 v[16:19], v[168:171], v[198:201], v[16:19]
	v_mfma_f32_16x16x32_bf16 v[4:7], v[146:149], v[220:223], v[4:7]
	v_mfma_f32_16x16x32_bf16 v[0:3], v[168:171], v[220:223], v[0:3]
	v_mfma_f32_16x16x32_bf16 v[54:57], v[150:153], v[186:189], v[54:57]
	v_mfma_f32_16x16x32_bf16 v[50:53], v[172:175], v[186:189], v[50:53]
	v_mfma_f32_16x16x32_bf16 v[36:39], v[150:153], v[194:197], v[36:39]
	v_mfma_f32_16x16x32_bf16 v[32:35], v[172:175], v[194:197], v[32:35]
	v_mfma_f32_16x16x32_bf16 v[20:23], v[150:153], v[216:219], v[20:23]
	v_mfma_f32_16x16x32_bf16 v[16:19], v[172:175], v[216:219], v[16:19]
	v_mfma_f32_16x16x32_bf16 v[4:7], v[150:153], v[224:227], v[4:7]
	v_mfma_f32_16x16x32_bf16 v[0:3], v[172:175], v[224:227], v[0:3]
	s_setprio 0
	s_barrier
	s_add_i32 s6, 0, 0x18000
	v_add_u32_e32 v48, s6, v183
	s_add_i32 s26, 0, 0x1c000
	ds_read_b128 v[122:125], v48
	ds_read_b128 v[130:133], v48 offset:1024
	ds_read_b128 v[138:141], v48 offset:2048
	ds_read_b128 v[142:145], v48 offset:3072
	v_add_u32_e32 v48, s26, v183
	ds_read_b128 v[146:149], v48
	ds_read_b128 v[150:153], v48 offset:1024
	ds_read_b128 v[168:171], v48 offset:2048
	ds_read_b128 v[172:175], v48 offset:3072
	s_add_u32 s20, s56, 0xb0000
	s_addc_u32 s21, s57, 0
	s_mov_b32 m0, s61
	v_lshl_add_u64 v[232:233], s[20:21], 0, v[156:157]
	ds_read_b128 v[176:179], v185 offset:32768
	ds_read_b128 v[186:189], v185 offset:33792
	ds_read_b128 v[190:193], v185 offset:34816
	ds_read_b128 v[194:197], v185 offset:35840
	ds_read_b128 v[198:201], v185 offset:36864
	ds_read_b128 v[216:219], v185 offset:37888
	ds_read_b128 v[220:223], v185 offset:38912
	ds_read_b128 v[224:227], v185 offset:39936
	global_load_lds_dwordx4 v[232:233], off
	v_lshl_add_u64 v[232:233], s[20:21], 0, v[160:161]
	s_mov_b32 m0, s62
	s_nop 0
	global_load_lds_dwordx4 v[232:233], off
	s_waitcnt vmcnt(8)
	s_waitcnt lgkmcnt(0)
	s_barrier
	s_setprio 1
	v_mfma_f32_16x16x32_bf16 v[134:137], v[122:125], v[176:179], v[134:137]
	v_mfma_f32_16x16x32_bf16 v[126:129], v[138:141], v[176:179], v[126:129]
	v_mfma_f32_16x16x32_bf16 v[110:113], v[122:125], v[190:193], v[110:113]
	v_mfma_f32_16x16x32_bf16 v[106:109], v[138:141], v[190:193], v[106:109]
	v_mfma_f32_16x16x32_bf16 v[94:97], v[122:125], v[198:201], v[94:97]
	v_mfma_f32_16x16x32_bf16 v[90:93], v[138:141], v[198:201], v[90:93]
	v_mfma_f32_16x16x32_bf16 v[78:81], v[122:125], v[220:223], v[78:81]
	v_mfma_f32_16x16x32_bf16 v[74:77], v[138:141], v[220:223], v[74:77]
	v_mfma_f32_16x16x32_bf16 v[134:137], v[130:133], v[186:189], v[134:137]
	v_mfma_f32_16x16x32_bf16 v[126:129], v[142:145], v[186:189], v[126:129]
	v_mfma_f32_16x16x32_bf16 v[110:113], v[130:133], v[194:197], v[110:113]
	v_mfma_f32_16x16x32_bf16 v[106:109], v[142:145], v[194:197], v[106:109]
	v_mfma_f32_16x16x32_bf16 v[94:97], v[130:133], v[216:219], v[94:97]
	v_mfma_f32_16x16x32_bf16 v[90:93], v[142:145], v[216:219], v[90:93]
	v_mfma_f32_16x16x32_bf16 v[78:81], v[130:133], v[224:227], v[78:81]
	v_mfma_f32_16x16x32_bf16 v[74:77], v[142:145], v[224:227], v[74:77]
	v_mfma_f32_16x16x32_bf16 v[118:121], v[146:149], v[176:179], v[118:121]
	v_mfma_f32_16x16x32_bf16 v[114:117], v[168:171], v[176:179], v[114:117]
	v_mfma_f32_16x16x32_bf16 v[102:105], v[146:149], v[190:193], v[102:105]
	v_mfma_f32_16x16x32_bf16 v[98:101], v[168:171], v[190:193], v[98:101]
	v_mfma_f32_16x16x32_bf16 v[86:89], v[146:149], v[198:201], v[86:89]
	v_mfma_f32_16x16x32_bf16 v[82:85], v[168:171], v[198:201], v[82:85]
	v_mfma_f32_16x16x32_bf16 v[70:73], v[146:149], v[220:223], v[70:73]
	v_mfma_f32_16x16x32_bf16 v[66:69], v[168:171], v[220:223], v[66:69]
	v_mfma_f32_16x16x32_bf16 v[118:121], v[150:153], v[186:189], v[118:121]
	v_mfma_f32_16x16x32_bf16 v[114:117], v[172:175], v[186:189], v[114:117]
	v_mfma_f32_16x16x32_bf16 v[102:105], v[150:153], v[194:197], v[102:105]
	v_mfma_f32_16x16x32_bf16 v[98:101], v[172:175], v[194:197], v[98:101]
	v_mfma_f32_16x16x32_bf16 v[86:89], v[150:153], v[216:219], v[86:89]
	v_mfma_f32_16x16x32_bf16 v[82:85], v[172:175], v[216:219], v[82:85]
	v_mfma_f32_16x16x32_bf16 v[70:73], v[150:153], v[224:227], v[70:73]
	v_mfma_f32_16x16x32_bf16 v[66:69], v[172:175], v[224:227], v[66:69]
	s_setprio 0
	s_barrier
	s_add_i32 s6, s6, s58
	v_lshl_add_u64 v[180:181], v[180:181], 0, s[30:31]
	s_mov_b32 m0, s6
	ds_read_b128 v[176:179], v185 offset:49152
	ds_read_b128 v[186:189], v185 offset:50176
	ds_read_b128 v[190:193], v185 offset:51200
	ds_read_b128 v[194:197], v185 offset:52224
	ds_read_b128 v[198:201], v185 offset:53248
	ds_read_b128 v[216:219], v185 offset:54272
	ds_read_b128 v[220:223], v185 offset:55296
	ds_read_b128 v[224:227], v185 offset:56320
	global_load_lds_dwordx4 v[180:181], off
	s_add_i32 m0, s6, 0x2000
	s_add_u32 s20, s54, 0xb0080
	v_lshl_add_u64 v[180:181], v[202:203], 0, s[30:31]
	s_addc_u32 s21, s55, 0
	s_add_i32 s6, s26, s58
	global_load_lds_dwordx4 v[180:181], off
	v_lshl_add_u64 v[180:181], s[20:21], 0, v[158:159]
	s_mov_b32 m0, s6
	s_nop 0
	global_load_lds_dwordx4 v[180:181], off
	v_lshl_add_u64 v[180:181], s[20:21], 0, v[162:163]
	s_add_i32 m0, s6, 0x2000
	s_nop 0
	global_load_lds_dwordx4 v[180:181], off
	v_lshl_add_u64 v[180:181], v[228:229], 0, s[30:31]
	s_mov_b32 m0, s63
	s_nop 0
	global_load_lds_dwordx4 v[180:181], off
	v_lshl_add_u64 v[180:181], v[230:231], 0, s[30:31]
	s_mov_b32 m0, s64
	s_nop 0
	global_load_lds_dwordx4 v[180:181], off
	s_waitcnt vmcnt(8)
	s_waitcnt lgkmcnt(0)
	s_barrier
	s_setprio 1
	v_mfma_f32_16x16x32_bf16 v[62:65], v[122:125], v[176:179], v[62:65]
	v_mfma_f32_16x16x32_bf16 v[58:61], v[138:141], v[176:179], v[58:61]
	v_mfma_f32_16x16x32_bf16 v[44:47], v[122:125], v[190:193], v[44:47]
	v_mfma_f32_16x16x32_bf16 v[40:43], v[138:141], v[190:193], v[40:43]
	v_mfma_f32_16x16x32_bf16 v[28:31], v[122:125], v[198:201], v[28:31]
	v_mfma_f32_16x16x32_bf16 v[24:27], v[138:141], v[198:201], v[24:27]
	v_mfma_f32_16x16x32_bf16 v[12:15], v[122:125], v[220:223], v[12:15]
	v_mfma_f32_16x16x32_bf16 v[8:11], v[138:141], v[220:223], v[8:11]
	v_mfma_f32_16x16x32_bf16 v[62:65], v[130:133], v[186:189], v[62:65]
	v_mfma_f32_16x16x32_bf16 v[58:61], v[142:145], v[186:189], v[58:61]
	v_mfma_f32_16x16x32_bf16 v[44:47], v[130:133], v[194:197], v[44:47]
	v_mfma_f32_16x16x32_bf16 v[40:43], v[142:145], v[194:197], v[40:43]
	v_mfma_f32_16x16x32_bf16 v[28:31], v[130:133], v[216:219], v[28:31]
	v_mfma_f32_16x16x32_bf16 v[24:27], v[142:145], v[216:219], v[24:27]
	v_mfma_f32_16x16x32_bf16 v[12:15], v[130:133], v[224:227], v[12:15]
	v_mfma_f32_16x16x32_bf16 v[8:11], v[142:145], v[224:227], v[8:11]
	v_mfma_f32_16x16x32_bf16 v[54:57], v[146:149], v[176:179], v[54:57]
	v_mfma_f32_16x16x32_bf16 v[50:53], v[168:171], v[176:179], v[50:53]
	v_mfma_f32_16x16x32_bf16 v[36:39], v[146:149], v[190:193], v[36:39]
	v_mfma_f32_16x16x32_bf16 v[32:35], v[168:171], v[190:193], v[32:35]
	v_mfma_f32_16x16x32_bf16 v[20:23], v[146:149], v[198:201], v[20:23]
	v_mfma_f32_16x16x32_bf16 v[16:19], v[168:171], v[198:201], v[16:19]
	v_mfma_f32_16x16x32_bf16 v[4:7], v[146:149], v[220:223], v[4:7]
	v_mfma_f32_16x16x32_bf16 v[0:3], v[168:171], v[220:223], v[0:3]
	v_mfma_f32_16x16x32_bf16 v[54:57], v[150:153], v[186:189], v[54:57]
	v_mfma_f32_16x16x32_bf16 v[50:53], v[172:175], v[186:189], v[50:53]
	v_mfma_f32_16x16x32_bf16 v[36:39], v[150:153], v[194:197], v[36:39]
	v_mfma_f32_16x16x32_bf16 v[32:35], v[172:175], v[194:197], v[32:35]
	v_mfma_f32_16x16x32_bf16 v[20:23], v[150:153], v[216:219], v[20:23]
	v_mfma_f32_16x16x32_bf16 v[16:19], v[172:175], v[216:219], v[16:19]
	v_mfma_f32_16x16x32_bf16 v[4:7], v[150:153], v[224:227], v[4:7]
	v_mfma_f32_16x16x32_bf16 v[0:3], v[172:175], v[224:227], v[0:3]
	s_setprio 0
	s_barrier
	s_add_i32 s71, s71, 2
	s_add_u32 s69, s69, 0x100
	s_addc_u32 s70, s70, 0
	s_cmp_gt_u32 s71, 41
	s_mov_b64 s[50:51], s[52:53]
	s_cbranch_scc0 .LBB0_472
	s_and_b64 vcc, exec, s[44:45]
	s_cbranch_vccz .LBB0_475
	s_barrier

.LBB0_585:
	s_add_u32 s6, s60, 0xfffc0080
	s_addc_u32 s20, s61, -1
	s_add_i32 s21, 0, 0x10000
	s_cmp_eq_u32 s90, 12
	s_cselect_b32 s65, s18, s20
	s_cselect_b32 s64, s33, s6
	v_add_u32_e32 v48, s21, v175
	s_cselect_b32 s63, s43, s53
	s_cselect_b32 s62, s45, s51
	s_add_i32 s6, 0, 0x14000
	ds_read_b128 v[142:145], v48
	ds_read_b128 v[146:149], v48 offset:1024
	ds_read_b128 v[150:153], v48 offset:2048
	ds_read_b128 v[156:159], v48 offset:3072
	v_add_u32_e32 v48, s6, v175
	ds_read_b128 v[160:163], v48
	ds_read_b128 v[164:167], v48 offset:1024
	ds_read_b128 v[168:171], v48 offset:2048
	ds_read_b128 v[180:183], v48 offset:3072
	v_lshl_add_u64 v[172:173], s[60:61], 0, v[138:139]
	s_add_i32 m0, s66, 0xc000
	ds_read_b128 v[184:187], v178
	ds_read_b128 v[188:191], v178 offset:1024
	ds_read_b128 v[192:195], v178 offset:2048
	ds_read_b128 v[196:199], v178 offset:3072
	ds_read_b128 v[200:203], v178 offset:4096
	ds_read_b128 v[216:219], v178 offset:5120
	ds_read_b128 v[220:223], v178 offset:6144
	ds_read_b128 v[224:227], v178 offset:7168
	global_load_lds_dwordx4 v[172:173], off
	v_lshl_add_u64 v[172:173], s[60:61], 0, v[140:141]
	s_add_i32 m0, s66, 0xe000
	s_nop 0
	global_load_lds_dwordx4 v[172:173], off
	s_waitcnt vmcnt(8)
	s_waitcnt lgkmcnt(0)
	s_barrier
	s_setprio 1
	v_mfma_f32_16x16x32_bf16 v[126:129], v[142:145], v[184:187], v[126:129]
	v_mfma_f32_16x16x32_bf16 v[122:125], v[150:153], v[184:187], v[122:125]
	v_mfma_f32_16x16x32_bf16 v[110:113], v[142:145], v[192:195], v[110:113]
	v_mfma_f32_16x16x32_bf16 v[106:109], v[150:153], v[192:195], v[106:109]
	v_mfma_f32_16x16x32_bf16 v[94:97], v[142:145], v[200:203], v[94:97]
	v_mfma_f32_16x16x32_bf16 v[90:93], v[150:153], v[200:203], v[90:93]
	v_mfma_f32_16x16x32_bf16 v[78:81], v[142:145], v[220:223], v[78:81]
	v_mfma_f32_16x16x32_bf16 v[74:77], v[150:153], v[220:223], v[74:77]
	v_mfma_f32_16x16x32_bf16 v[126:129], v[146:149], v[188:191], v[126:129]
	v_mfma_f32_16x16x32_bf16 v[122:125], v[156:159], v[188:191], v[122:125]
	v_mfma_f32_16x16x32_bf16 v[110:113], v[146:149], v[196:199], v[110:113]
	v_mfma_f32_16x16x32_bf16 v[106:109], v[156:159], v[196:199], v[106:109]
	v_mfma_f32_16x16x32_bf16 v[94:97], v[146:149], v[216:219], v[94:97]
	v_mfma_f32_16x16x32_bf16 v[90:93], v[156:159], v[216:219], v[90:93]
	v_mfma_f32_16x16x32_bf16 v[78:81], v[146:149], v[224:227], v[78:81]
	v_mfma_f32_16x16x32_bf16 v[74:77], v[156:159], v[224:227], v[74:77]
	v_mfma_f32_16x16x32_bf16 v[118:121], v[160:163], v[184:187], v[118:121]
	v_mfma_f32_16x16x32_bf16 v[114:117], v[168:171], v[184:187], v[114:117]
	v_mfma_f32_16x16x32_bf16 v[102:105], v[160:163], v[192:195], v[102:105]
	v_mfma_f32_16x16x32_bf16 v[98:101], v[168:171], v[192:195], v[98:101]
	v_mfma_f32_16x16x32_bf16 v[86:89], v[160:163], v[200:203], v[86:89]
	v_mfma_f32_16x16x32_bf16 v[82:85], v[168:171], v[200:203], v[82:85]
	v_mfma_f32_16x16x32_bf16 v[70:73], v[160:163], v[220:223], v[70:73]
	v_mfma_f32_16x16x32_bf16 v[66:69], v[168:171], v[220:223], v[66:69]
	v_mfma_f32_16x16x32_bf16 v[118:121], v[164:167], v[188:191], v[118:121]
	v_mfma_f32_16x16x32_bf16 v[114:117], v[180:183], v[188:191], v[114:117]
	v_mfma_f32_16x16x32_bf16 v[102:105], v[164:167], v[196:199], v[102:105]
	v_mfma_f32_16x16x32_bf16 v[98:101], v[180:183], v[196:199], v[98:101]
	v_mfma_f32_16x16x32_bf16 v[86:89], v[164:167], v[216:219], v[86:89]
	v_mfma_f32_16x16x32_bf16 v[82:85], v[180:183], v[216:219], v[82:85]
	v_mfma_f32_16x16x32_bf16 v[70:73], v[164:167], v[224:227], v[70:73]
	v_mfma_f32_16x16x32_bf16 v[66:69], v[180:183], v[224:227], v[66:69]
	s_setprio 0
	s_barrier
	s_add_i32 s20, s21, s24
	v_lshl_add_u64 v[172:173], s[62:63], 0, v[132:133]
	s_mov_b32 m0, s20
	ds_read_b128 v[184:187], v178 offset:16384
	ds_read_b128 v[188:191], v178 offset:17408
	ds_read_b128 v[192:195], v178 offset:18432
	ds_read_b128 v[196:199], v178 offset:19456
	ds_read_b128 v[200:203], v178 offset:20480
	ds_read_b128 v[216:219], v178 offset:21504
	ds_read_b128 v[220:223], v178 offset:22528
	ds_read_b128 v[224:227], v178 offset:23552
	global_load_lds_dwordx4 v[172:173], off
	s_add_i32 m0, s20, 0x2000
	s_add_u32 s20, s62, 0x40000
	v_lshl_add_u64 v[228:229], s[62:63], 0, v[136:137]
	s_addc_u32 s21, s63, 0
	s_add_i32 s6, s6, s24
	global_load_lds_dwordx4 v[228:229], off
	v_lshl_add_u64 v[230:231], s[20:21], 0, v[132:133]
	s_mov_b32 m0, s6
	v_lshl_add_u64 v[232:233], s[64:65], 0, v[134:135]
	global_load_lds_dwordx4 v[230:231], off
	v_lshl_add_u64 v[230:231], s[20:21], 0, v[136:137]
	s_add_i32 m0, s6, 0x2000
	s_nop 0
	global_load_lds_dwordx4 v[230:231], off
	v_lshl_add_u64 v[230:231], s[64:65], 0, v[130:131]
	s_mov_b32 m0, s66
	s_nop 0
	global_load_lds_dwordx4 v[230:231], off
	s_mov_b32 m0, s67
	s_nop 0
	global_load_lds_dwordx4 v[232:233], off
	s_waitcnt vmcnt(8)
	s_waitcnt lgkmcnt(0)
	s_barrier
	s_setprio 1
	v_mfma_f32_16x16x32_bf16 v[62:65], v[142:145], v[184:187], v[62:65]
	v_mfma_f32_16x16x32_bf16 v[58:61], v[150:153], v[184:187], v[58:61]
	v_mfma_f32_16x16x32_bf16 v[44:47], v[142:145], v[192:195], v[44:47]
	v_mfma_f32_16x16x32_bf16 v[40:43], v[150:153], v[192:195], v[40:43]
	v_mfma_f32_16x16x32_bf16 v[28:31], v[142:145], v[200:203], v[28:31]
	v_mfma_f32_16x16x32_bf16 v[24:27], v[150:153], v[200:203], v[24:27]
	v_mfma_f32_16x16x32_bf16 v[12:15], v[142:145], v[220:223], v[12:15]
	v_mfma_f32_16x16x32_bf16 v[8:11], v[150:153], v[220:223], v[8:11]
	v_mfma_f32_16x16x32_bf16 v[62:65], v[146:149], v[188:191], v[62:65]
	v_mfma_f32_16x16x32_bf16 v[58:61], v[156:159], v[188:191], v[58:61]
	v_mfma_f32_16x16x32_bf16 v[44:47], v[146:149], v[196:199], v[44:47]
	v_mfma_f32_16x16x32_bf16 v[40:43], v[156:159], v[196:199], v[40:43]
	v_mfma_f32_16x16x32_bf16 v[28:31], v[146:149], v[216:219], v[28:31]
	v_mfma_f32_16x16x32_bf16 v[24:27], v[156:159], v[216:219], v[24:27]
	v_mfma_f32_16x16x32_bf16 v[12:15], v[146:149], v[224:227], v[12:15]
	v_mfma_f32_16x16x32_bf16 v[8:11], v[156:159], v[224:227], v[8:11]
	v_mfma_f32_16x16x32_bf16 v[54:57], v[160:163], v[184:187], v[54:57]
	v_mfma_f32_16x16x32_bf16 v[50:53], v[168:171], v[184:187], v[50:53]
	v_mfma_f32_16x16x32_bf16 v[36:39], v[160:163], v[192:195], v[36:39]
	v_mfma_f32_16x16x32_bf16 v[32:35], v[168:171], v[192:195], v[32:35]
	v_mfma_f32_16x16x32_bf16 v[20:23], v[160:163], v[200:203], v[20:23]
	v_mfma_f32_16x16x32_bf16 v[16:19], v[168:171], v[200:203], v[16:19]
	v_mfma_f32_16x16x32_bf16 v[4:7], v[160:163], v[220:223], v[4:7]
	v_mfma_f32_16x16x32_bf16 v[0:3], v[168:171], v[220:223], v[0:3]
	v_mfma_f32_16x16x32_bf16 v[54:57], v[164:167], v[188:191], v[54:57]
	v_mfma_f32_16x16x32_bf16 v[50:53], v[180:183], v[188:191], v[50:53]
	v_mfma_f32_16x16x32_bf16 v[36:39], v[164:167], v[196:199], v[36:39]
	v_mfma_f32_16x16x32_bf16 v[32:35], v[180:183], v[196:199], v[32:35]
	v_mfma_f32_16x16x32_bf16 v[20:23], v[164:167], v[216:219], v[20:23]
	v_mfma_f32_16x16x32_bf16 v[16:19], v[180:183], v[216:219], v[16:19]
	v_mfma_f32_16x16x32_bf16 v[4:7], v[164:167], v[224:227], v[4:7]
	v_mfma_f32_16x16x32_bf16 v[0:3], v[180:183], v[224:227], v[0:3]
	s_setprio 0
	s_barrier
	s_add_i32 s6, 0, 0x18000
	v_add_u32_e32 v48, s6, v175
	s_add_i32 s26, 0, 0x1c000
	ds_read_b128 v[142:145], v48
	ds_read_b128 v[146:149], v48 offset:1024
	ds_read_b128 v[150:153], v48 offset:2048
	ds_read_b128 v[156:159], v48 offset:3072
	v_add_u32_e32 v48, s26, v175
	ds_read_b128 v[160:163], v48
	ds_read_b128 v[164:167], v48 offset:1024
	ds_read_b128 v[168:171], v48 offset:2048
	ds_read_b128 v[180:183], v48 offset:3072
	s_add_u32 s20, s64, 0x40000
	s_addc_u32 s21, s65, 0
	s_mov_b32 m0, s68
	v_lshl_add_u64 v[234:235], s[20:21], 0, v[130:131]
	ds_read_b128 v[184:187], v178 offset:32768
	ds_read_b128 v[188:191], v178 offset:33792
	ds_read_b128 v[192:195], v178 offset:34816
	ds_read_b128 v[196:199], v178 offset:35840
	ds_read_b128 v[200:203], v178 offset:36864
	ds_read_b128 v[216:219], v178 offset:37888
	ds_read_b128 v[220:223], v178 offset:38912
	ds_read_b128 v[224:227], v178 offset:39936
	global_load_lds_dwordx4 v[234:235], off
	v_lshl_add_u64 v[234:235], s[20:21], 0, v[134:135]
	s_mov_b32 m0, s69
	s_nop 0
	global_load_lds_dwordx4 v[234:235], off
	s_waitcnt vmcnt(8)
	s_waitcnt lgkmcnt(0)
	s_barrier
	s_setprio 1
	v_mfma_f32_16x16x32_bf16 v[126:129], v[142:145], v[184:187], v[126:129]
	v_mfma_f32_16x16x32_bf16 v[122:125], v[150:153], v[184:187], v[122:125]
	v_mfma_f32_16x16x32_bf16 v[110:113], v[142:145], v[192:195], v[110:113]
	v_mfma_f32_16x16x32_bf16 v[106:109], v[150:153], v[192:195], v[106:109]
	v_mfma_f32_16x16x32_bf16 v[94:97], v[142:145], v[200:203], v[94:97]
	v_mfma_f32_16x16x32_bf16 v[90:93], v[150:153], v[200:203], v[90:93]
	v_mfma_f32_16x16x32_bf16 v[78:81], v[142:145], v[220:223], v[78:81]
	v_mfma_f32_16x16x32_bf16 v[74:77], v[150:153], v[220:223], v[74:77]
	v_mfma_f32_16x16x32_bf16 v[126:129], v[146:149], v[188:191], v[126:129]
	v_mfma_f32_16x16x32_bf16 v[122:125], v[156:159], v[188:191], v[122:125]
	v_mfma_f32_16x16x32_bf16 v[110:113], v[146:149], v[196:199], v[110:113]
	v_mfma_f32_16x16x32_bf16 v[106:109], v[156:159], v[196:199], v[106:109]
	v_mfma_f32_16x16x32_bf16 v[94:97], v[146:149], v[216:219], v[94:97]
	v_mfma_f32_16x16x32_bf16 v[90:93], v[156:159], v[216:219], v[90:93]
	v_mfma_f32_16x16x32_bf16 v[78:81], v[146:149], v[224:227], v[78:81]
	v_mfma_f32_16x16x32_bf16 v[74:77], v[156:159], v[224:227], v[74:77]
	v_mfma_f32_16x16x32_bf16 v[118:121], v[160:163], v[184:187], v[118:121]
	v_mfma_f32_16x16x32_bf16 v[114:117], v[168:171], v[184:187], v[114:117]
	v_mfma_f32_16x16x32_bf16 v[102:105], v[160:163], v[192:195], v[102:105]
	v_mfma_f32_16x16x32_bf16 v[98:101], v[168:171], v[192:195], v[98:101]
	v_mfma_f32_16x16x32_bf16 v[86:89], v[160:163], v[200:203], v[86:89]
	v_mfma_f32_16x16x32_bf16 v[82:85], v[168:171], v[200:203], v[82:85]
	v_mfma_f32_16x16x32_bf16 v[70:73], v[160:163], v[220:223], v[70:73]
	v_mfma_f32_16x16x32_bf16 v[66:69], v[168:171], v[220:223], v[66:69]
	v_mfma_f32_16x16x32_bf16 v[118:121], v[164:167], v[188:191], v[118:121]
	v_mfma_f32_16x16x32_bf16 v[114:117], v[180:183], v[188:191], v[114:117]
	v_mfma_f32_16x16x32_bf16 v[102:105], v[164:167], v[196:199], v[102:105]
	v_mfma_f32_16x16x32_bf16 v[98:101], v[180:183], v[196:199], v[98:101]
	v_mfma_f32_16x16x32_bf16 v[86:89], v[164:167], v[216:219], v[86:89]
	v_mfma_f32_16x16x32_bf16 v[82:85], v[180:183], v[216:219], v[82:85]
	v_mfma_f32_16x16x32_bf16 v[70:73], v[164:167], v[224:227], v[70:73]
	v_mfma_f32_16x16x32_bf16 v[66:69], v[180:183], v[224:227], v[66:69]
	s_setprio 0
	s_barrier
	s_add_i32 s6, s6, s24
	v_lshl_add_u64 v[172:173], v[172:173], 0, s[30:31]
	s_mov_b32 m0, s6
	ds_read_b128 v[184:187], v178 offset:49152
	ds_read_b128 v[188:191], v178 offset:50176
	ds_read_b128 v[192:195], v178 offset:51200
	ds_read_b128 v[196:199], v178 offset:52224
	ds_read_b128 v[200:203], v178 offset:53248
	ds_read_b128 v[216:219], v178 offset:54272
	ds_read_b128 v[220:223], v178 offset:55296
	ds_read_b128 v[224:227], v178 offset:56320
	global_load_lds_dwordx4 v[172:173], off
	s_add_i32 m0, s6, 0x2000
	s_add_u32 s20, s62, 0x40080
	v_lshl_add_u64 v[172:173], v[228:229], 0, s[30:31]
	s_addc_u32 s21, s63, 0
	s_add_i32 s6, s26, s24
	global_load_lds_dwordx4 v[172:173], off
	v_lshl_add_u64 v[172:173], s[20:21], 0, v[132:133]
	s_mov_b32 m0, s6
	s_nop 0
	global_load_lds_dwordx4 v[172:173], off
	v_lshl_add_u64 v[172:173], s[20:21], 0, v[136:137]
	s_add_i32 m0, s6, 0x2000
	s_nop 0
	global_load_lds_dwordx4 v[172:173], off
	v_lshl_add_u64 v[172:173], v[230:231], 0, s[30:31]
	s_mov_b32 m0, s70
	s_nop 0
	global_load_lds_dwordx4 v[172:173], off
	v_lshl_add_u64 v[172:173], v[232:233], 0, s[30:31]
	s_mov_b32 m0, s71
	s_nop 0
	global_load_lds_dwordx4 v[172:173], off
	s_waitcnt vmcnt(8)
	s_waitcnt lgkmcnt(0)
	s_barrier
	s_setprio 1
	v_mfma_f32_16x16x32_bf16 v[62:65], v[142:145], v[184:187], v[62:65]
	v_mfma_f32_16x16x32_bf16 v[58:61], v[150:153], v[184:187], v[58:61]
	v_mfma_f32_16x16x32_bf16 v[44:47], v[142:145], v[192:195], v[44:47]
	v_mfma_f32_16x16x32_bf16 v[40:43], v[150:153], v[192:195], v[40:43]
	v_mfma_f32_16x16x32_bf16 v[28:31], v[142:145], v[200:203], v[28:31]
	v_mfma_f32_16x16x32_bf16 v[24:27], v[150:153], v[200:203], v[24:27]
	v_mfma_f32_16x16x32_bf16 v[12:15], v[142:145], v[220:223], v[12:15]
	v_mfma_f32_16x16x32_bf16 v[8:11], v[150:153], v[220:223], v[8:11]
	v_mfma_f32_16x16x32_bf16 v[62:65], v[146:149], v[188:191], v[62:65]
	v_mfma_f32_16x16x32_bf16 v[58:61], v[156:159], v[188:191], v[58:61]
	v_mfma_f32_16x16x32_bf16 v[44:47], v[146:149], v[196:199], v[44:47]
	v_mfma_f32_16x16x32_bf16 v[40:43], v[156:159], v[196:199], v[40:43]
	v_mfma_f32_16x16x32_bf16 v[28:31], v[146:149], v[216:219], v[28:31]
	v_mfma_f32_16x16x32_bf16 v[24:27], v[156:159], v[216:219], v[24:27]
	v_mfma_f32_16x16x32_bf16 v[12:15], v[146:149], v[224:227], v[12:15]
	v_mfma_f32_16x16x32_bf16 v[8:11], v[156:159], v[224:227], v[8:11]
	v_mfma_f32_16x16x32_bf16 v[54:57], v[160:163], v[184:187], v[54:57]
	v_mfma_f32_16x16x32_bf16 v[50:53], v[168:171], v[184:187], v[50:53]
	v_mfma_f32_16x16x32_bf16 v[36:39], v[160:163], v[192:195], v[36:39]
	v_mfma_f32_16x16x32_bf16 v[32:35], v[168:171], v[192:195], v[32:35]
	v_mfma_f32_16x16x32_bf16 v[20:23], v[160:163], v[200:203], v[20:23]
	v_mfma_f32_16x16x32_bf16 v[16:19], v[168:171], v[200:203], v[16:19]
	v_mfma_f32_16x16x32_bf16 v[4:7], v[160:163], v[220:223], v[4:7]
	v_mfma_f32_16x16x32_bf16 v[0:3], v[168:171], v[220:223], v[0:3]
	v_mfma_f32_16x16x32_bf16 v[54:57], v[164:167], v[188:191], v[54:57]
	v_mfma_f32_16x16x32_bf16 v[50:53], v[180:183], v[188:191], v[50:53]
	v_mfma_f32_16x16x32_bf16 v[36:39], v[164:167], v[196:199], v[36:39]
	v_mfma_f32_16x16x32_bf16 v[32:35], v[180:183], v[196:199], v[32:35]
	v_mfma_f32_16x16x32_bf16 v[20:23], v[164:167], v[216:219], v[20:23]
	v_mfma_f32_16x16x32_bf16 v[16:19], v[180:183], v[216:219], v[16:19]
	v_mfma_f32_16x16x32_bf16 v[4:7], v[164:167], v[224:227], v[4:7]
	v_mfma_f32_16x16x32_bf16 v[0:3], v[180:183], v[224:227], v[0:3]
	s_setprio 0
	s_barrier
	s_add_i32 s90, s90, 2
	s_add_u32 s60, s60, 0x100
	s_addc_u32 s61, s61, 0
	s_add_u32 s51, s51, 0x100
	s_addc_u32 s53, s53, 0
	s_cmp_gt_u32 s90, 13
	s_cbranch_scc0 .LBB0_585
	s_and_b64 vcc, exec, s[48:49]
	s_cbranch_vccz .LBB0_588
	s_barrier

.LBB0_690:
	s_add_u32 s6, s56, 0xfffc0080
	s_addc_u32 s20, s57, -1
	s_add_i32 s21, 0, 0x10000
	s_cmp_eq_u32 s71, 12
	s_cselect_b32 s61, s41, s20
	s_cselect_b32 s60, s47, s6
	v_add_u32_e32 v48, s21, v177
	s_cselect_b32 s59, s49, s70
	s_cselect_b32 s58, s68, s69
	s_add_i32 s6, 0, 0x14000
	ds_read_b128 v[142:145], v48
	ds_read_b128 v[146:149], v48 offset:1024
	ds_read_b128 v[150:153], v48 offset:2048
	ds_read_b128 v[156:159], v48 offset:3072
	v_add_u32_e32 v48, s6, v177
	ds_read_b128 v[160:163], v48
	ds_read_b128 v[164:167], v48 offset:1024
	ds_read_b128 v[168:171], v48 offset:2048
	ds_read_b128 v[172:175], v48 offset:3072
	v_lshl_add_u64 v[202:203], s[56:57], 0, v[138:139]
	s_add_i32 m0, s63, 0xc000
	ds_read_b128 v[182:185], v180
	ds_read_b128 v[186:189], v180 offset:1024
	ds_read_b128 v[190:193], v180 offset:2048
	ds_read_b128 v[194:197], v180 offset:3072
	ds_read_b128 v[198:201], v180 offset:4096
	ds_read_b128 v[216:219], v180 offset:5120
	ds_read_b128 v[220:223], v180 offset:6144
	ds_read_b128 v[224:227], v180 offset:7168
	global_load_lds_dwordx4 v[202:203], off
	v_lshl_add_u64 v[202:203], s[56:57], 0, v[140:141]
	s_add_i32 m0, s63, 0xe000
	s_nop 0
	global_load_lds_dwordx4 v[202:203], off
	s_waitcnt vmcnt(8)
	s_waitcnt lgkmcnt(0)
	s_barrier
	s_setprio 1
	v_mfma_f32_16x16x32_bf16 v[126:129], v[142:145], v[182:185], v[126:129]
	v_mfma_f32_16x16x32_bf16 v[122:125], v[150:153], v[182:185], v[122:125]
	v_mfma_f32_16x16x32_bf16 v[118:121], v[142:145], v[190:193], v[118:121]
	v_mfma_f32_16x16x32_bf16 v[110:113], v[150:153], v[190:193], v[110:113]
	v_mfma_f32_16x16x32_bf16 v[102:105], v[142:145], v[198:201], v[102:105]
	v_mfma_f32_16x16x32_bf16 v[94:97], v[150:153], v[198:201], v[94:97]
	v_mfma_f32_16x16x32_bf16 v[86:89], v[142:145], v[220:223], v[86:89]
	v_mfma_f32_16x16x32_bf16 v[78:81], v[150:153], v[220:223], v[78:81]
	v_mfma_f32_16x16x32_bf16 v[126:129], v[146:149], v[186:189], v[126:129]
	v_mfma_f32_16x16x32_bf16 v[122:125], v[156:159], v[186:189], v[122:125]
	v_mfma_f32_16x16x32_bf16 v[118:121], v[146:149], v[194:197], v[118:121]
	v_mfma_f32_16x16x32_bf16 v[110:113], v[156:159], v[194:197], v[110:113]
	v_mfma_f32_16x16x32_bf16 v[102:105], v[146:149], v[216:219], v[102:105]
	v_mfma_f32_16x16x32_bf16 v[94:97], v[156:159], v[216:219], v[94:97]
	v_mfma_f32_16x16x32_bf16 v[86:89], v[146:149], v[224:227], v[86:89]
	v_mfma_f32_16x16x32_bf16 v[78:81], v[156:159], v[224:227], v[78:81]
	v_mfma_f32_16x16x32_bf16 v[114:117], v[160:163], v[182:185], v[114:117]
	v_mfma_f32_16x16x32_bf16 v[106:109], v[168:171], v[182:185], v[106:109]
	v_mfma_f32_16x16x32_bf16 v[98:101], v[160:163], v[190:193], v[98:101]
	v_mfma_f32_16x16x32_bf16 v[90:93], v[168:171], v[190:193], v[90:93]
	v_mfma_f32_16x16x32_bf16 v[82:85], v[160:163], v[198:201], v[82:85]
	v_mfma_f32_16x16x32_bf16 v[74:77], v[168:171], v[198:201], v[74:77]
	v_mfma_f32_16x16x32_bf16 v[70:73], v[160:163], v[220:223], v[70:73]
	v_mfma_f32_16x16x32_bf16 v[66:69], v[168:171], v[220:223], v[66:69]
	v_mfma_f32_16x16x32_bf16 v[114:117], v[164:167], v[186:189], v[114:117]
	v_mfma_f32_16x16x32_bf16 v[106:109], v[172:175], v[186:189], v[106:109]
	v_mfma_f32_16x16x32_bf16 v[98:101], v[164:167], v[194:197], v[98:101]
	v_mfma_f32_16x16x32_bf16 v[90:93], v[172:175], v[194:197], v[90:93]
	v_mfma_f32_16x16x32_bf16 v[82:85], v[164:167], v[216:219], v[82:85]
	v_mfma_f32_16x16x32_bf16 v[74:77], v[172:175], v[216:219], v[74:77]
	v_mfma_f32_16x16x32_bf16 v[70:73], v[164:167], v[224:227], v[70:73]
	v_mfma_f32_16x16x32_bf16 v[66:69], v[172:175], v[224:227], v[66:69]
	s_setprio 0
	s_barrier
	s_add_i32 s20, s21, s62
	v_lshl_add_u64 v[202:203], s[58:59], 0, v[134:135]
	s_mov_b32 m0, s20
	ds_read_b128 v[182:185], v180 offset:16384
	ds_read_b128 v[186:189], v180 offset:17408
	ds_read_b128 v[190:193], v180 offset:18432
	ds_read_b128 v[194:197], v180 offset:19456
	ds_read_b128 v[198:201], v180 offset:20480
	ds_read_b128 v[216:219], v180 offset:21504
	ds_read_b128 v[220:223], v180 offset:22528
	ds_read_b128 v[224:227], v180 offset:23552
	global_load_lds_dwordx4 v[202:203], off
	s_add_i32 m0, s20, 0x2000
	s_add_u32 s20, s58, 0x40000
	v_lshl_add_u64 v[228:229], s[58:59], 0, v[130:131]
	s_addc_u32 s21, s59, 0
	s_add_i32 s6, s6, s62
	global_load_lds_dwordx4 v[228:229], off
	v_lshl_add_u64 v[230:231], s[20:21], 0, v[134:135]
	s_mov_b32 m0, s6
	v_lshl_add_u64 v[232:233], s[60:61], 0, v[132:133]
	global_load_lds_dwordx4 v[230:231], off
	v_lshl_add_u64 v[230:231], s[20:21], 0, v[130:131]
	s_add_i32 m0, s6, 0x2000
	s_nop 0
	global_load_lds_dwordx4 v[230:231], off
	v_lshl_add_u64 v[230:231], s[60:61], 0, v[136:137]
	s_mov_b32 m0, s63
	s_nop 0
	global_load_lds_dwordx4 v[230:231], off
	s_mov_b32 m0, s64
	s_nop 0
	global_load_lds_dwordx4 v[232:233], off
	s_waitcnt vmcnt(8)
	s_waitcnt lgkmcnt(0)
	s_barrier
	s_setprio 1
	v_mfma_f32_16x16x32_bf16 v[62:65], v[142:145], v[182:185], v[62:65]
	v_mfma_f32_16x16x32_bf16 v[58:61], v[150:153], v[182:185], v[58:61]
	v_mfma_f32_16x16x32_bf16 v[54:57], v[142:145], v[190:193], v[54:57]
	v_mfma_f32_16x16x32_bf16 v[44:47], v[150:153], v[190:193], v[44:47]
	v_mfma_f32_16x16x32_bf16 v[36:39], v[142:145], v[198:201], v[36:39]
	v_mfma_f32_16x16x32_bf16 v[28:31], v[150:153], v[198:201], v[28:31]
	v_mfma_f32_16x16x32_bf16 v[20:23], v[142:145], v[220:223], v[20:23]
	v_mfma_f32_16x16x32_bf16 v[12:15], v[150:153], v[220:223], v[12:15]
	v_mfma_f32_16x16x32_bf16 v[62:65], v[146:149], v[186:189], v[62:65]
	v_mfma_f32_16x16x32_bf16 v[58:61], v[156:159], v[186:189], v[58:61]
	v_mfma_f32_16x16x32_bf16 v[54:57], v[146:149], v[194:197], v[54:57]
	v_mfma_f32_16x16x32_bf16 v[44:47], v[156:159], v[194:197], v[44:47]
	v_mfma_f32_16x16x32_bf16 v[36:39], v[146:149], v[216:219], v[36:39]
	v_mfma_f32_16x16x32_bf16 v[28:31], v[156:159], v[216:219], v[28:31]
	v_mfma_f32_16x16x32_bf16 v[20:23], v[146:149], v[224:227], v[20:23]
	v_mfma_f32_16x16x32_bf16 v[12:15], v[156:159], v[224:227], v[12:15]
	v_mfma_f32_16x16x32_bf16 v[50:53], v[160:163], v[182:185], v[50:53]
	v_mfma_f32_16x16x32_bf16 v[40:43], v[168:171], v[182:185], v[40:43]
	v_mfma_f32_16x16x32_bf16 v[32:35], v[160:163], v[190:193], v[32:35]
	v_mfma_f32_16x16x32_bf16 v[24:27], v[168:171], v[190:193], v[24:27]
	v_mfma_f32_16x16x32_bf16 v[16:19], v[160:163], v[198:201], v[16:19]
	v_mfma_f32_16x16x32_bf16 v[8:11], v[168:171], v[198:201], v[8:11]
	v_mfma_f32_16x16x32_bf16 v[4:7], v[160:163], v[220:223], v[4:7]
	v_mfma_f32_16x16x32_bf16 v[0:3], v[168:171], v[220:223], v[0:3]
	v_mfma_f32_16x16x32_bf16 v[50:53], v[164:167], v[186:189], v[50:53]
	v_mfma_f32_16x16x32_bf16 v[40:43], v[172:175], v[186:189], v[40:43]
	v_mfma_f32_16x16x32_bf16 v[32:35], v[164:167], v[194:197], v[32:35]
	v_mfma_f32_16x16x32_bf16 v[24:27], v[172:175], v[194:197], v[24:27]
	v_mfma_f32_16x16x32_bf16 v[16:19], v[164:167], v[216:219], v[16:19]
	v_mfma_f32_16x16x32_bf16 v[8:11], v[172:175], v[216:219], v[8:11]
	v_mfma_f32_16x16x32_bf16 v[4:7], v[164:167], v[224:227], v[4:7]
	v_mfma_f32_16x16x32_bf16 v[0:3], v[172:175], v[224:227], v[0:3]
	s_setprio 0
	s_barrier
	s_add_i32 s6, 0, 0x18000
	v_add_u32_e32 v48, s6, v177
	s_add_i32 s26, 0, 0x1c000
	ds_read_b128 v[142:145], v48
	ds_read_b128 v[146:149], v48 offset:1024
	ds_read_b128 v[150:153], v48 offset:2048
	ds_read_b128 v[156:159], v48 offset:3072
	v_add_u32_e32 v48, s26, v177
	ds_read_b128 v[160:163], v48
	ds_read_b128 v[164:167], v48 offset:1024
	ds_read_b128 v[168:171], v48 offset:2048
	ds_read_b128 v[172:175], v48 offset:3072
	s_add_u32 s20, s60, 0x40000
	s_addc_u32 s21, s61, 0
	s_mov_b32 m0, s65
	v_lshl_add_u64 v[234:235], s[20:21], 0, v[136:137]
	ds_read_b128 v[182:185], v180 offset:32768
	ds_read_b128 v[186:189], v180 offset:33792
	ds_read_b128 v[190:193], v180 offset:34816
	ds_read_b128 v[194:197], v180 offset:35840
	ds_read_b128 v[198:201], v180 offset:36864
	ds_read_b128 v[216:219], v180 offset:37888
	ds_read_b128 v[220:223], v180 offset:38912
	ds_read_b128 v[224:227], v180 offset:39936
	global_load_lds_dwordx4 v[234:235], off
	v_lshl_add_u64 v[234:235], s[20:21], 0, v[132:133]
	s_mov_b32 m0, s66
	s_nop 0
	global_load_lds_dwordx4 v[234:235], off
	s_waitcnt vmcnt(8)
	s_waitcnt lgkmcnt(0)
	s_barrier
	s_setprio 1
	v_mfma_f32_16x16x32_bf16 v[126:129], v[142:145], v[182:185], v[126:129]
	v_mfma_f32_16x16x32_bf16 v[122:125], v[150:153], v[182:185], v[122:125]
	v_mfma_f32_16x16x32_bf16 v[118:121], v[142:145], v[190:193], v[118:121]
	v_mfma_f32_16x16x32_bf16 v[110:113], v[150:153], v[190:193], v[110:113]
	v_mfma_f32_16x16x32_bf16 v[102:105], v[142:145], v[198:201], v[102:105]
	v_mfma_f32_16x16x32_bf16 v[94:97], v[150:153], v[198:201], v[94:97]
	v_mfma_f32_16x16x32_bf16 v[86:89], v[142:145], v[220:223], v[86:89]
	v_mfma_f32_16x16x32_bf16 v[78:81], v[150:153], v[220:223], v[78:81]
	v_mfma_f32_16x16x32_bf16 v[126:129], v[146:149], v[186:189], v[126:129]
	v_mfma_f32_16x16x32_bf16 v[122:125], v[156:159], v[186:189], v[122:125]
	v_mfma_f32_16x16x32_bf16 v[118:121], v[146:149], v[194:197], v[118:121]
	v_mfma_f32_16x16x32_bf16 v[110:113], v[156:159], v[194:197], v[110:113]
	v_mfma_f32_16x16x32_bf16 v[102:105], v[146:149], v[216:219], v[102:105]
	v_mfma_f32_16x16x32_bf16 v[94:97], v[156:159], v[216:219], v[94:97]
	v_mfma_f32_16x16x32_bf16 v[86:89], v[146:149], v[224:227], v[86:89]
	v_mfma_f32_16x16x32_bf16 v[78:81], v[156:159], v[224:227], v[78:81]
	v_mfma_f32_16x16x32_bf16 v[114:117], v[160:163], v[182:185], v[114:117]
	v_mfma_f32_16x16x32_bf16 v[106:109], v[168:171], v[182:185], v[106:109]
	v_mfma_f32_16x16x32_bf16 v[98:101], v[160:163], v[190:193], v[98:101]
	v_mfma_f32_16x16x32_bf16 v[90:93], v[168:171], v[190:193], v[90:93]
	v_mfma_f32_16x16x32_bf16 v[82:85], v[160:163], v[198:201], v[82:85]
	v_mfma_f32_16x16x32_bf16 v[74:77], v[168:171], v[198:201], v[74:77]
	v_mfma_f32_16x16x32_bf16 v[70:73], v[160:163], v[220:223], v[70:73]
	v_mfma_f32_16x16x32_bf16 v[66:69], v[168:171], v[220:223], v[66:69]
	v_mfma_f32_16x16x32_bf16 v[114:117], v[164:167], v[186:189], v[114:117]
	v_mfma_f32_16x16x32_bf16 v[106:109], v[172:175], v[186:189], v[106:109]
	v_mfma_f32_16x16x32_bf16 v[98:101], v[164:167], v[194:197], v[98:101]
	v_mfma_f32_16x16x32_bf16 v[90:93], v[172:175], v[194:197], v[90:93]
	v_mfma_f32_16x16x32_bf16 v[82:85], v[164:167], v[216:219], v[82:85]
	v_mfma_f32_16x16x32_bf16 v[74:77], v[172:175], v[216:219], v[74:77]
	v_mfma_f32_16x16x32_bf16 v[70:73], v[164:167], v[224:227], v[70:73]
	v_mfma_f32_16x16x32_bf16 v[66:69], v[172:175], v[224:227], v[66:69]
	s_setprio 0
	s_barrier
	s_add_i32 s6, s6, s62
	v_lshl_add_u64 v[202:203], v[202:203], 0, s[30:31]
	s_mov_b32 m0, s6
	ds_read_b128 v[182:185], v180 offset:49152
	ds_read_b128 v[186:189], v180 offset:50176
	ds_read_b128 v[190:193], v180 offset:51200
	ds_read_b128 v[194:197], v180 offset:52224
	ds_read_b128 v[198:201], v180 offset:53248
	ds_read_b128 v[216:219], v180 offset:54272
	ds_read_b128 v[220:223], v180 offset:55296
	ds_read_b128 v[224:227], v180 offset:56320
	global_load_lds_dwordx4 v[202:203], off
	s_add_i32 m0, s6, 0x2000
	s_add_u32 s20, s58, 0x40080
	v_lshl_add_u64 v[202:203], v[228:229], 0, s[30:31]
	s_addc_u32 s21, s59, 0
	s_add_i32 s6, s26, s62
	global_load_lds_dwordx4 v[202:203], off
	v_lshl_add_u64 v[202:203], s[20:21], 0, v[134:135]
	s_mov_b32 m0, s6
	s_nop 0
	global_load_lds_dwordx4 v[202:203], off
	v_lshl_add_u64 v[202:203], s[20:21], 0, v[130:131]
	s_add_i32 m0, s6, 0x2000
	s_nop 0
	global_load_lds_dwordx4 v[202:203], off
	v_lshl_add_u64 v[202:203], v[230:231], 0, s[30:31]
	s_mov_b32 m0, s18
	s_nop 0
	global_load_lds_dwordx4 v[202:203], off
	v_lshl_add_u64 v[202:203], v[232:233], 0, s[30:31]
	s_mov_b32 m0, s24
	s_nop 0
	global_load_lds_dwordx4 v[202:203], off
	s_waitcnt vmcnt(8)
	s_waitcnt lgkmcnt(0)
	s_barrier
	s_setprio 1
	v_mfma_f32_16x16x32_bf16 v[62:65], v[142:145], v[182:185], v[62:65]
	v_mfma_f32_16x16x32_bf16 v[58:61], v[150:153], v[182:185], v[58:61]
	v_mfma_f32_16x16x32_bf16 v[54:57], v[142:145], v[190:193], v[54:57]
	v_mfma_f32_16x16x32_bf16 v[44:47], v[150:153], v[190:193], v[44:47]
	v_mfma_f32_16x16x32_bf16 v[36:39], v[142:145], v[198:201], v[36:39]
	v_mfma_f32_16x16x32_bf16 v[28:31], v[150:153], v[198:201], v[28:31]
	v_mfma_f32_16x16x32_bf16 v[20:23], v[142:145], v[220:223], v[20:23]
	v_mfma_f32_16x16x32_bf16 v[12:15], v[150:153], v[220:223], v[12:15]
	v_mfma_f32_16x16x32_bf16 v[62:65], v[146:149], v[186:189], v[62:65]
	v_mfma_f32_16x16x32_bf16 v[58:61], v[156:159], v[186:189], v[58:61]
	v_mfma_f32_16x16x32_bf16 v[54:57], v[146:149], v[194:197], v[54:57]
	v_mfma_f32_16x16x32_bf16 v[44:47], v[156:159], v[194:197], v[44:47]
	v_mfma_f32_16x16x32_bf16 v[36:39], v[146:149], v[216:219], v[36:39]
	v_mfma_f32_16x16x32_bf16 v[28:31], v[156:159], v[216:219], v[28:31]
	v_mfma_f32_16x16x32_bf16 v[20:23], v[146:149], v[224:227], v[20:23]
	v_mfma_f32_16x16x32_bf16 v[12:15], v[156:159], v[224:227], v[12:15]
	v_mfma_f32_16x16x32_bf16 v[50:53], v[160:163], v[182:185], v[50:53]
	v_mfma_f32_16x16x32_bf16 v[40:43], v[168:171], v[182:185], v[40:43]
	v_mfma_f32_16x16x32_bf16 v[32:35], v[160:163], v[190:193], v[32:35]
	v_mfma_f32_16x16x32_bf16 v[24:27], v[168:171], v[190:193], v[24:27]
	v_mfma_f32_16x16x32_bf16 v[16:19], v[160:163], v[198:201], v[16:19]
	v_mfma_f32_16x16x32_bf16 v[8:11], v[168:171], v[198:201], v[8:11]
	v_mfma_f32_16x16x32_bf16 v[4:7], v[160:163], v[220:223], v[4:7]
	v_mfma_f32_16x16x32_bf16 v[0:3], v[168:171], v[220:223], v[0:3]
	v_mfma_f32_16x16x32_bf16 v[50:53], v[164:167], v[186:189], v[50:53]
	v_mfma_f32_16x16x32_bf16 v[40:43], v[172:175], v[186:189], v[40:43]
	v_mfma_f32_16x16x32_bf16 v[32:35], v[164:167], v[194:197], v[32:35]
	v_mfma_f32_16x16x32_bf16 v[24:27], v[172:175], v[194:197], v[24:27]
	v_mfma_f32_16x16x32_bf16 v[16:19], v[164:167], v[216:219], v[16:19]
	v_mfma_f32_16x16x32_bf16 v[8:11], v[172:175], v[216:219], v[8:11]
	v_mfma_f32_16x16x32_bf16 v[4:7], v[164:167], v[224:227], v[4:7]
	v_mfma_f32_16x16x32_bf16 v[0:3], v[172:175], v[224:227], v[0:3]
	s_setprio 0
	s_barrier
	s_add_i32 s71, s71, 2
	s_add_u32 s56, s56, 0x100
	s_addc_u32 s57, s57, 0
	s_add_u32 s69, s69, 0x100
	s_addc_u32 s70, s70, 0
	s_cmp_gt_u32 s71, 13
	s_cbranch_scc0 .LBB0_690
	s_and_b64 vcc, exec, s[44:45]
	s_cbranch_vccz .LBB0_693
	s_barrier

.LBB0_789:
	s_cmp_eq_u32 s18, 2
	s_cselect_b64 vcc, -1, 0
	s_add_i32 s6, 0, 0x10000
	v_add_u32_e32 v48, s6, v170
	s_add_i32 s7, 0, 0x14000
	ds_read_b128 v[158:161], v48
	ds_read_b128 v[162:165], v48 offset:1024
	ds_read_b128 v[178:181], v48 offset:2048
	ds_read_b128 v[182:185], v48 offset:3072
	v_add_u32_e32 v48, s7, v170
	ds_read_b128 v[186:189], v48
	ds_read_b128 v[190:193], v48 offset:1024
	ds_read_b128 v[194:197], v48 offset:2048
	ds_read_b128 v[198:201], v48 offset:3072
	v_lshl_add_u64 v[152:153], v[150:151], 0, s[34:35]
	v_cndmask_b32_e32 v203, v153, v145, vcc
	v_cndmask_b32_e32 v202, v152, v144, vcc
	v_cndmask_b32_e32 v249, v149, v147, vcc
	v_cndmask_b32_e32 v248, v148, v146, vcc
	v_lshl_add_u64 v[250:251], v[150:151], 0, v[140:141]
	s_add_i32 m0, s9, 0xc000
	ds_read_b128 v[216:219], v174
	ds_read_b128 v[220:223], v174 offset:1024
	ds_read_b128 v[224:227], v174 offset:2048
	ds_read_b128 v[228:231], v174 offset:3072
	ds_read_b128 v[232:235], v174 offset:4096
	ds_read_b128 v[236:239], v174 offset:5120
	ds_read_b128 v[240:243], v174 offset:6144
	ds_read_b128 v[244:247], v174 offset:7168
	global_load_lds_dwordx4 v[250:251], off
	v_lshl_add_u64 v[150:151], v[150:151], 0, v[142:143]
	s_add_i32 m0, s9, 0xe000
	s_nop 0
	global_load_lds_dwordx4 v[150:151], off
	s_waitcnt vmcnt(8)
	s_waitcnt lgkmcnt(0)
	s_barrier
	s_setprio 1
	v_mfma_f32_16x16x32_bf16 v[126:129], v[158:161], v[216:219], v[126:129]
	v_mfma_f32_16x16x32_bf16 v[122:125], v[178:181], v[216:219], v[122:125]
	v_mfma_f32_16x16x32_bf16 v[118:121], v[158:161], v[224:227], v[118:121]
	v_mfma_f32_16x16x32_bf16 v[114:117], v[178:181], v[224:227], v[114:117]
	v_mfma_f32_16x16x32_bf16 v[110:113], v[158:161], v[232:235], v[110:113]
	v_mfma_f32_16x16x32_bf16 v[106:109], v[178:181], v[232:235], v[106:109]
	v_mfma_f32_16x16x32_bf16 v[102:105], v[158:161], v[240:243], v[102:105]
	v_mfma_f32_16x16x32_bf16 v[98:101], v[178:181], v[240:243], v[98:101]
	v_mfma_f32_16x16x32_bf16 v[126:129], v[162:165], v[220:223], v[126:129]
	v_mfma_f32_16x16x32_bf16 v[122:125], v[182:185], v[220:223], v[122:125]
	v_mfma_f32_16x16x32_bf16 v[118:121], v[162:165], v[228:231], v[118:121]
	v_mfma_f32_16x16x32_bf16 v[114:117], v[182:185], v[228:231], v[114:117]
	v_mfma_f32_16x16x32_bf16 v[110:113], v[162:165], v[236:239], v[110:113]
	v_mfma_f32_16x16x32_bf16 v[106:109], v[182:185], v[236:239], v[106:109]
	v_mfma_f32_16x16x32_bf16 v[102:105], v[162:165], v[244:247], v[102:105]
	v_mfma_f32_16x16x32_bf16 v[98:101], v[182:185], v[244:247], v[98:101]
	v_mfma_f32_16x16x32_bf16 v[62:65], v[186:189], v[216:219], v[62:65]
	v_mfma_f32_16x16x32_bf16 v[58:61], v[194:197], v[216:219], v[58:61]
	v_mfma_f32_16x16x32_bf16 v[54:57], v[186:189], v[224:227], v[54:57]
	v_mfma_f32_16x16x32_bf16 v[50:53], v[194:197], v[224:227], v[50:53]
	v_mfma_f32_16x16x32_bf16 v[44:47], v[186:189], v[232:235], v[44:47]
	v_mfma_f32_16x16x32_bf16 v[40:43], v[194:197], v[232:235], v[40:43]
	v_mfma_f32_16x16x32_bf16 v[36:39], v[186:189], v[240:243], v[36:39]
	v_mfma_f32_16x16x32_bf16 v[32:35], v[194:197], v[240:243], v[32:35]
	v_mfma_f32_16x16x32_bf16 v[62:65], v[190:193], v[220:223], v[62:65]
	v_mfma_f32_16x16x32_bf16 v[58:61], v[198:201], v[220:223], v[58:61]
	v_mfma_f32_16x16x32_bf16 v[54:57], v[190:193], v[228:231], v[54:57]
	v_mfma_f32_16x16x32_bf16 v[50:53], v[198:201], v[228:231], v[50:53]
	v_mfma_f32_16x16x32_bf16 v[44:47], v[190:193], v[236:239], v[44:47]
	v_mfma_f32_16x16x32_bf16 v[40:43], v[198:201], v[236:239], v[40:43]
	v_mfma_f32_16x16x32_bf16 v[36:39], v[190:193], v[244:247], v[36:39]
	v_mfma_f32_16x16x32_bf16 v[32:35], v[198:201], v[244:247], v[32:35]
	s_setprio 0
	s_barrier
	s_add_i32 s6, s6, s8
	v_lshl_add_u64 v[150:151], v[248:249], 0, v[134:135]
	s_mov_b32 m0, s6
	ds_read_b128 v[216:219], v174 offset:16384
	ds_read_b128 v[220:223], v174 offset:17408
	ds_read_b128 v[224:227], v174 offset:18432
	ds_read_b128 v[228:231], v174 offset:19456
	ds_read_b128 v[232:235], v174 offset:20480
	ds_read_b128 v[236:239], v174 offset:21504
	ds_read_b128 v[240:243], v174 offset:22528
	ds_read_b128 v[244:247], v174 offset:23552
	global_load_lds_dwordx4 v[150:151], off
	v_lshl_add_u64 v[250:251], v[248:249], 0, v[138:139]
	s_add_i32 m0, s6, 0x2000
	v_lshl_add_u64 v[252:253], v[248:249], 0, s[4:5]
	s_add_i32 s6, s7, s8
	global_load_lds_dwordx4 v[250:251], off
	v_lshl_add_u64 v[214:215], v[252:253], 0, v[134:135]
	s_mov_b32 m0, s6
	s_nop 0
	global_load_lds_dwordx4 v[214:215], off
	v_lshl_add_u64 v[214:215], v[252:253], 0, v[138:139]
	s_add_i32 m0, s6, 0x2000
	v_lshl_add_u64 v[252:253], v[202:203], 0, v[136:137]
	global_load_lds_dwordx4 v[214:215], off
	v_lshl_add_u64 v[214:215], v[202:203], 0, v[132:133]
	s_mov_b32 m0, s9
	s_nop 0
	global_load_lds_dwordx4 v[214:215], off
	s_mov_b32 m0, s24
	s_nop 0
	global_load_lds_dwordx4 v[252:253], off
	s_waitcnt vmcnt(8)
	s_waitcnt lgkmcnt(0)
	s_barrier
	s_setprio 1
	v_mfma_f32_16x16x32_bf16 v[94:97], v[158:161], v[216:219], v[94:97]
	v_mfma_f32_16x16x32_bf16 v[90:93], v[178:181], v[216:219], v[90:93]
	v_mfma_f32_16x16x32_bf16 v[86:89], v[158:161], v[224:227], v[86:89]
	v_mfma_f32_16x16x32_bf16 v[82:85], v[178:181], v[224:227], v[82:85]
	v_mfma_f32_16x16x32_bf16 v[78:81], v[158:161], v[232:235], v[78:81]
	v_mfma_f32_16x16x32_bf16 v[74:77], v[178:181], v[232:235], v[74:77]
	v_mfma_f32_16x16x32_bf16 v[70:73], v[158:161], v[240:243], v[70:73]
	v_mfma_f32_16x16x32_bf16 v[66:69], v[178:181], v[240:243], v[66:69]
	v_mfma_f32_16x16x32_bf16 v[94:97], v[162:165], v[220:223], v[94:97]
	v_mfma_f32_16x16x32_bf16 v[90:93], v[182:185], v[220:223], v[90:93]
	v_mfma_f32_16x16x32_bf16 v[86:89], v[162:165], v[228:231], v[86:89]
	v_mfma_f32_16x16x32_bf16 v[82:85], v[182:185], v[228:231], v[82:85]
	v_mfma_f32_16x16x32_bf16 v[78:81], v[162:165], v[236:239], v[78:81]
	v_mfma_f32_16x16x32_bf16 v[74:77], v[182:185], v[236:239], v[74:77]
	v_mfma_f32_16x16x32_bf16 v[70:73], v[162:165], v[244:247], v[70:73]
	v_mfma_f32_16x16x32_bf16 v[66:69], v[182:185], v[244:247], v[66:69]
	v_mfma_f32_16x16x32_bf16 v[28:31], v[186:189], v[216:219], v[28:31]
	v_mfma_f32_16x16x32_bf16 v[24:27], v[194:197], v[216:219], v[24:27]
	v_mfma_f32_16x16x32_bf16 v[20:23], v[186:189], v[224:227], v[20:23]
	v_mfma_f32_16x16x32_bf16 v[16:19], v[194:197], v[224:227], v[16:19]
	v_mfma_f32_16x16x32_bf16 v[12:15], v[186:189], v[232:235], v[12:15]
	v_mfma_f32_16x16x32_bf16 v[8:11], v[194:197], v[232:235], v[8:11]
	v_mfma_f32_16x16x32_bf16 v[4:7], v[186:189], v[240:243], v[4:7]
	v_mfma_f32_16x16x32_bf16 v[0:3], v[194:197], v[240:243], v[0:3]
	v_mfma_f32_16x16x32_bf16 v[28:31], v[190:193], v[220:223], v[28:31]
	v_mfma_f32_16x16x32_bf16 v[24:27], v[198:201], v[220:223], v[24:27]
	v_mfma_f32_16x16x32_bf16 v[20:23], v[190:193], v[228:231], v[20:23]
	v_mfma_f32_16x16x32_bf16 v[16:19], v[198:201], v[228:231], v[16:19]
	v_mfma_f32_16x16x32_bf16 v[12:15], v[190:193], v[236:239], v[12:15]
	v_mfma_f32_16x16x32_bf16 v[8:11], v[198:201], v[236:239], v[8:11]
	v_mfma_f32_16x16x32_bf16 v[4:7], v[190:193], v[244:247], v[4:7]
	v_mfma_f32_16x16x32_bf16 v[0:3], v[198:201], v[244:247], v[0:3]
	s_setprio 0
	s_barrier
	s_add_i32 s6, 0, 0x18000
	v_add_u32_e32 v48, s6, v170
	s_add_i32 s7, 0, 0x1c000
	ds_read_b128 v[158:161], v48
	ds_read_b128 v[162:165], v48 offset:1024
	ds_read_b128 v[178:181], v48 offset:2048
	ds_read_b128 v[182:185], v48 offset:3072
	v_add_u32_e32 v48, s7, v170
	ds_read_b128 v[186:189], v48
	ds_read_b128 v[190:193], v48 offset:1024
	ds_read_b128 v[194:197], v48 offset:2048
	ds_read_b128 v[198:201], v48 offset:3072
	v_lshl_add_u64 v[202:203], v[202:203], 0, s[10:11]
	s_mov_b32 m0, s86
	v_lshl_add_u64 v[212:213], v[202:203], 0, v[132:133]
	ds_read_b128 v[216:219], v174 offset:32768
	ds_read_b128 v[220:223], v174 offset:33792
	ds_read_b128 v[224:227], v174 offset:34816
	ds_read_b128 v[228:231], v174 offset:35840
	ds_read_b128 v[232:235], v174 offset:36864
	ds_read_b128 v[236:239], v174 offset:37888
	ds_read_b128 v[240:243], v174 offset:38912
	ds_read_b128 v[244:247], v174 offset:39936
	global_load_lds_dwordx4 v[212:213], off
	v_lshl_add_u64 v[202:203], v[202:203], 0, v[136:137]
	s_mov_b32 m0, s87
	s_nop 0
	global_load_lds_dwordx4 v[202:203], off
	s_waitcnt vmcnt(8)
	s_waitcnt lgkmcnt(0)
	s_barrier
	s_setprio 1
	v_mfma_f32_16x16x32_bf16 v[126:129], v[158:161], v[216:219], v[126:129]
	v_mfma_f32_16x16x32_bf16 v[122:125], v[178:181], v[216:219], v[122:125]
	v_mfma_f32_16x16x32_bf16 v[118:121], v[158:161], v[224:227], v[118:121]
	v_mfma_f32_16x16x32_bf16 v[114:117], v[178:181], v[224:227], v[114:117]
	v_mfma_f32_16x16x32_bf16 v[110:113], v[158:161], v[232:235], v[110:113]
	v_mfma_f32_16x16x32_bf16 v[106:109], v[178:181], v[232:235], v[106:109]
	v_mfma_f32_16x16x32_bf16 v[102:105], v[158:161], v[240:243], v[102:105]
	v_mfma_f32_16x16x32_bf16 v[98:101], v[178:181], v[240:243], v[98:101]
	v_mfma_f32_16x16x32_bf16 v[126:129], v[162:165], v[220:223], v[126:129]
	v_mfma_f32_16x16x32_bf16 v[122:125], v[182:185], v[220:223], v[122:125]
	v_mfma_f32_16x16x32_bf16 v[118:121], v[162:165], v[228:231], v[118:121]
	v_mfma_f32_16x16x32_bf16 v[114:117], v[182:185], v[228:231], v[114:117]
	v_mfma_f32_16x16x32_bf16 v[110:113], v[162:165], v[236:239], v[110:113]
	v_mfma_f32_16x16x32_bf16 v[106:109], v[182:185], v[236:239], v[106:109]
	v_mfma_f32_16x16x32_bf16 v[102:105], v[162:165], v[244:247], v[102:105]
	v_mfma_f32_16x16x32_bf16 v[98:101], v[182:185], v[244:247], v[98:101]
	v_mfma_f32_16x16x32_bf16 v[62:65], v[186:189], v[216:219], v[62:65]
	v_mfma_f32_16x16x32_bf16 v[58:61], v[194:197], v[216:219], v[58:61]
	v_mfma_f32_16x16x32_bf16 v[54:57], v[186:189], v[224:227], v[54:57]
	v_mfma_f32_16x16x32_bf16 v[50:53], v[194:197], v[224:227], v[50:53]
	v_mfma_f32_16x16x32_bf16 v[44:47], v[186:189], v[232:235], v[44:47]
	v_mfma_f32_16x16x32_bf16 v[40:43], v[194:197], v[232:235], v[40:43]
	v_mfma_f32_16x16x32_bf16 v[36:39], v[186:189], v[240:243], v[36:39]
	v_mfma_f32_16x16x32_bf16 v[32:35], v[194:197], v[240:243], v[32:35]
	v_mfma_f32_16x16x32_bf16 v[62:65], v[190:193], v[220:223], v[62:65]
	v_mfma_f32_16x16x32_bf16 v[58:61], v[198:201], v[220:223], v[58:61]
	v_mfma_f32_16x16x32_bf16 v[54:57], v[190:193], v[228:231], v[54:57]
	v_mfma_f32_16x16x32_bf16 v[50:53], v[198:201], v[228:231], v[50:53]
	v_mfma_f32_16x16x32_bf16 v[44:47], v[190:193], v[236:239], v[44:47]
	v_mfma_f32_16x16x32_bf16 v[40:43], v[198:201], v[236:239], v[40:43]
	v_mfma_f32_16x16x32_bf16 v[36:39], v[190:193], v[244:247], v[36:39]
	v_mfma_f32_16x16x32_bf16 v[32:35], v[198:201], v[244:247], v[32:35]
	s_setprio 0
	s_barrier
	s_add_i32 s6, s6, s8
	v_lshl_add_u64 v[150:151], v[150:151], 0, s[30:31]
	s_mov_b32 m0, s6
	ds_read_b128 v[216:219], v174 offset:49152
	ds_read_b128 v[220:223], v174 offset:50176
	ds_read_b128 v[224:227], v174 offset:51200
	ds_read_b128 v[228:231], v174 offset:52224
	ds_read_b128 v[232:235], v174 offset:53248
	ds_read_b128 v[236:239], v174 offset:54272
	ds_read_b128 v[240:243], v174 offset:55296
	ds_read_b128 v[244:247], v174 offset:56320
	global_load_lds_dwordx4 v[150:151], off
	v_lshl_add_u64 v[150:151], v[250:251], 0, s[30:31]
	s_add_i32 m0, s6, 0x2000
	s_add_i32 s6, s7, s8
	global_load_lds_dwordx4 v[150:151], off
	v_lshl_add_u64 v[150:151], v[248:249], 0, s[14:15]
	v_lshl_add_u64 v[202:203], v[150:151], 0, v[134:135]
	s_mov_b32 m0, s6
	v_lshl_add_u64 v[150:151], v[150:151], 0, v[138:139]
	global_load_lds_dwordx4 v[202:203], off
	s_add_i32 m0, s6, 0x2000
	s_nop 0
	global_load_lds_dwordx4 v[150:151], off
	v_lshl_add_u64 v[150:151], v[214:215], 0, s[30:31]
	s_mov_b32 m0, s89
	s_nop 0
	global_load_lds_dwordx4 v[150:151], off
	v_lshl_add_u64 v[150:151], v[252:253], 0, s[30:31]
	s_mov_b32 m0, s90
	s_nop 0
	global_load_lds_dwordx4 v[150:151], off
	s_waitcnt vmcnt(8)
	s_waitcnt lgkmcnt(0)
	s_barrier
	s_setprio 1
	v_mfma_f32_16x16x32_bf16 v[94:97], v[158:161], v[216:219], v[94:97]
	v_mfma_f32_16x16x32_bf16 v[90:93], v[178:181], v[216:219], v[90:93]
	v_mfma_f32_16x16x32_bf16 v[86:89], v[158:161], v[224:227], v[86:89]
	v_mfma_f32_16x16x32_bf16 v[82:85], v[178:181], v[224:227], v[82:85]
	v_mfma_f32_16x16x32_bf16 v[78:81], v[158:161], v[232:235], v[78:81]
	v_mfma_f32_16x16x32_bf16 v[74:77], v[178:181], v[232:235], v[74:77]
	v_mfma_f32_16x16x32_bf16 v[70:73], v[158:161], v[240:243], v[70:73]
	v_mfma_f32_16x16x32_bf16 v[66:69], v[178:181], v[240:243], v[66:69]
	v_mfma_f32_16x16x32_bf16 v[94:97], v[162:165], v[220:223], v[94:97]
	v_mfma_f32_16x16x32_bf16 v[90:93], v[182:185], v[220:223], v[90:93]
	v_mfma_f32_16x16x32_bf16 v[86:89], v[162:165], v[228:231], v[86:89]
	v_mfma_f32_16x16x32_bf16 v[82:85], v[182:185], v[228:231], v[82:85]
	v_mfma_f32_16x16x32_bf16 v[78:81], v[162:165], v[236:239], v[78:81]
	v_mfma_f32_16x16x32_bf16 v[74:77], v[182:185], v[236:239], v[74:77]
	v_mfma_f32_16x16x32_bf16 v[70:73], v[162:165], v[244:247], v[70:73]
	v_mfma_f32_16x16x32_bf16 v[66:69], v[182:185], v[244:247], v[66:69]
	v_mfma_f32_16x16x32_bf16 v[28:31], v[186:189], v[216:219], v[28:31]
	v_mfma_f32_16x16x32_bf16 v[24:27], v[194:197], v[216:219], v[24:27]
	v_mfma_f32_16x16x32_bf16 v[20:23], v[186:189], v[224:227], v[20:23]
	v_mfma_f32_16x16x32_bf16 v[16:19], v[194:197], v[224:227], v[16:19]
	v_mfma_f32_16x16x32_bf16 v[12:15], v[186:189], v[232:235], v[12:15]
	v_mfma_f32_16x16x32_bf16 v[8:11], v[194:197], v[232:235], v[8:11]
	v_mfma_f32_16x16x32_bf16 v[4:7], v[186:189], v[240:243], v[4:7]
	v_mfma_f32_16x16x32_bf16 v[0:3], v[194:197], v[240:243], v[0:3]
	v_mfma_f32_16x16x32_bf16 v[28:31], v[190:193], v[220:223], v[28:31]
	v_mfma_f32_16x16x32_bf16 v[24:27], v[198:201], v[220:223], v[24:27]
	v_mfma_f32_16x16x32_bf16 v[20:23], v[190:193], v[228:231], v[20:23]
	v_mfma_f32_16x16x32_bf16 v[16:19], v[198:201], v[228:231], v[16:19]
	v_mfma_f32_16x16x32_bf16 v[12:15], v[190:193], v[236:239], v[12:15]
	v_mfma_f32_16x16x32_bf16 v[8:11], v[198:201], v[236:239], v[8:11]
	v_mfma_f32_16x16x32_bf16 v[4:7], v[190:193], v[244:247], v[4:7]
	v_mfma_f32_16x16x32_bf16 v[0:3], v[198:201], v[244:247], v[0:3]
	s_setprio 0
	s_barrier
	s_add_i32 s18, s18, 2
	v_lshl_add_u64 v[148:149], v[148:149], 0, s[34:35]
	s_cmp_gt_u32 s18, 3
	v_mov_b64_e32 v[150:151], v[152:153]
	s_cbranch_scc0 .LBB0_789
	s_and_b64 vcc, exec, s[64:65]
	s_cbranch_vccz .LBB0_792
	s_barrier

.LBB0_1301:
	s_add_u32 s6, s56, 0xfffc0080
	s_addc_u32 s20, s57, -1
	s_add_i32 s21, 0, 0x10000
	s_cmp_eq_u32 s70, 12
	s_cselect_b32 s61, s18, s20
	s_cselect_b32 s60, s33, s6
	v_add_u32_e32 v48, s21, v183
	s_cselect_b32 s59, s45, s69
	s_cselect_b32 s58, s47, s53
	s_add_i32 s6, 0, 0x14000
	ds_read_b128 v[122:125], v48
	ds_read_b128 v[130:133], v48 offset:1024
	ds_read_b128 v[138:141], v48 offset:2048
	ds_read_b128 v[142:145], v48 offset:3072
	v_add_u32_e32 v48, s6, v183
	ds_read_b128 v[146:149], v48
	ds_read_b128 v[150:153], v48 offset:1024
	ds_read_b128 v[168:171], v48 offset:2048
	ds_read_b128 v[172:175], v48 offset:3072
	v_lshl_add_u64 v[180:181], s[56:57], 0, v[164:165]
	s_add_i32 m0, s55, 0xc000
	ds_read_b128 v[176:179], v185
	ds_read_b128 v[186:189], v185 offset:1024
	ds_read_b128 v[190:193], v185 offset:2048
	ds_read_b128 v[194:197], v185 offset:3072
	ds_read_b128 v[198:201], v185 offset:4096
	ds_read_b128 v[216:219], v185 offset:5120
	ds_read_b128 v[220:223], v185 offset:6144
	ds_read_b128 v[224:227], v185 offset:7168
	global_load_lds_dwordx4 v[180:181], off
	v_lshl_add_u64 v[180:181], s[56:57], 0, v[166:167]
	s_add_i32 m0, s55, 0xe000
	s_nop 0
	global_load_lds_dwordx4 v[180:181], off
	s_waitcnt vmcnt(8)
	s_waitcnt lgkmcnt(0)
	s_barrier
	s_setprio 1
	v_mfma_f32_16x16x32_bf16 v[134:137], v[122:125], v[176:179], v[134:137]
	v_mfma_f32_16x16x32_bf16 v[126:129], v[138:141], v[176:179], v[126:129]
	v_mfma_f32_16x16x32_bf16 v[110:113], v[122:125], v[190:193], v[110:113]
	v_mfma_f32_16x16x32_bf16 v[106:109], v[138:141], v[190:193], v[106:109]
	v_mfma_f32_16x16x32_bf16 v[94:97], v[122:125], v[198:201], v[94:97]
	v_mfma_f32_16x16x32_bf16 v[90:93], v[138:141], v[198:201], v[90:93]
	v_mfma_f32_16x16x32_bf16 v[78:81], v[122:125], v[220:223], v[78:81]
	v_mfma_f32_16x16x32_bf16 v[74:77], v[138:141], v[220:223], v[74:77]
	v_mfma_f32_16x16x32_bf16 v[134:137], v[130:133], v[186:189], v[134:137]
	v_mfma_f32_16x16x32_bf16 v[126:129], v[142:145], v[186:189], v[126:129]
	v_mfma_f32_16x16x32_bf16 v[110:113], v[130:133], v[194:197], v[110:113]
	v_mfma_f32_16x16x32_bf16 v[106:109], v[142:145], v[194:197], v[106:109]
	v_mfma_f32_16x16x32_bf16 v[94:97], v[130:133], v[216:219], v[94:97]
	v_mfma_f32_16x16x32_bf16 v[90:93], v[142:145], v[216:219], v[90:93]
	v_mfma_f32_16x16x32_bf16 v[78:81], v[130:133], v[224:227], v[78:81]
	v_mfma_f32_16x16x32_bf16 v[74:77], v[142:145], v[224:227], v[74:77]
	v_mfma_f32_16x16x32_bf16 v[118:121], v[146:149], v[176:179], v[118:121]
	v_mfma_f32_16x16x32_bf16 v[114:117], v[168:171], v[176:179], v[114:117]
	v_mfma_f32_16x16x32_bf16 v[102:105], v[146:149], v[190:193], v[102:105]
	v_mfma_f32_16x16x32_bf16 v[98:101], v[168:171], v[190:193], v[98:101]
	v_mfma_f32_16x16x32_bf16 v[86:89], v[146:149], v[198:201], v[86:89]
	v_mfma_f32_16x16x32_bf16 v[82:85], v[168:171], v[198:201], v[82:85]
	v_mfma_f32_16x16x32_bf16 v[70:73], v[146:149], v[220:223], v[70:73]
	v_mfma_f32_16x16x32_bf16 v[66:69], v[168:171], v[220:223], v[66:69]
	v_mfma_f32_16x16x32_bf16 v[118:121], v[150:153], v[186:189], v[118:121]
	v_mfma_f32_16x16x32_bf16 v[114:117], v[172:175], v[186:189], v[114:117]
	v_mfma_f32_16x16x32_bf16 v[102:105], v[150:153], v[194:197], v[102:105]
	v_mfma_f32_16x16x32_bf16 v[98:101], v[172:175], v[194:197], v[98:101]
	v_mfma_f32_16x16x32_bf16 v[86:89], v[150:153], v[216:219], v[86:89]
	v_mfma_f32_16x16x32_bf16 v[82:85], v[172:175], v[216:219], v[82:85]
	v_mfma_f32_16x16x32_bf16 v[70:73], v[150:153], v[224:227], v[70:73]
	v_mfma_f32_16x16x32_bf16 v[66:69], v[172:175], v[224:227], v[66:69]
	s_setprio 0
	s_barrier
	s_add_i32 s20, s21, s24
	v_lshl_add_u64 v[180:181], s[58:59], 0, v[158:159]
	s_mov_b32 m0, s20
	ds_read_b128 v[176:179], v185 offset:16384
	ds_read_b128 v[186:189], v185 offset:17408
	ds_read_b128 v[190:193], v185 offset:18432
	ds_read_b128 v[194:197], v185 offset:19456
	ds_read_b128 v[198:201], v185 offset:20480
	ds_read_b128 v[216:219], v185 offset:21504
	ds_read_b128 v[220:223], v185 offset:22528
	ds_read_b128 v[224:227], v185 offset:23552
	global_load_lds_dwordx4 v[180:181], off
	s_add_i32 m0, s20, 0x2000
	s_add_u32 s20, s58, 0x40000
	v_lshl_add_u64 v[202:203], s[58:59], 0, v[162:163]
	s_addc_u32 s21, s59, 0
	s_add_i32 s6, s6, s24
	global_load_lds_dwordx4 v[202:203], off
	v_lshl_add_u64 v[212:213], s[20:21], 0, v[158:159]
	s_mov_b32 m0, s6
	v_lshl_add_u64 v[214:215], s[60:61], 0, v[160:161]
	global_load_lds_dwordx4 v[212:213], off
	v_lshl_add_u64 v[212:213], s[20:21], 0, v[162:163]
	s_add_i32 m0, s6, 0x2000
	s_nop 0
	global_load_lds_dwordx4 v[212:213], off
	v_lshl_add_u64 v[212:213], s[60:61], 0, v[156:157]
	s_mov_b32 m0, s55
	s_nop 0
	global_load_lds_dwordx4 v[212:213], off
	s_mov_b32 m0, s62
	s_nop 0
	global_load_lds_dwordx4 v[214:215], off
	s_waitcnt vmcnt(8)
	s_waitcnt lgkmcnt(0)
	s_barrier
	s_setprio 1
	v_mfma_f32_16x16x32_bf16 v[62:65], v[122:125], v[176:179], v[62:65]
	v_mfma_f32_16x16x32_bf16 v[58:61], v[138:141], v[176:179], v[58:61]
	v_mfma_f32_16x16x32_bf16 v[44:47], v[122:125], v[190:193], v[44:47]
	v_mfma_f32_16x16x32_bf16 v[40:43], v[138:141], v[190:193], v[40:43]
	v_mfma_f32_16x16x32_bf16 v[28:31], v[122:125], v[198:201], v[28:31]
	v_mfma_f32_16x16x32_bf16 v[24:27], v[138:141], v[198:201], v[24:27]
	v_mfma_f32_16x16x32_bf16 v[12:15], v[122:125], v[220:223], v[12:15]
	v_mfma_f32_16x16x32_bf16 v[8:11], v[138:141], v[220:223], v[8:11]
	v_mfma_f32_16x16x32_bf16 v[62:65], v[130:133], v[186:189], v[62:65]
	v_mfma_f32_16x16x32_bf16 v[58:61], v[142:145], v[186:189], v[58:61]
	v_mfma_f32_16x16x32_bf16 v[44:47], v[130:133], v[194:197], v[44:47]
	v_mfma_f32_16x16x32_bf16 v[40:43], v[142:145], v[194:197], v[40:43]
	v_mfma_f32_16x16x32_bf16 v[28:31], v[130:133], v[216:219], v[28:31]
	v_mfma_f32_16x16x32_bf16 v[24:27], v[142:145], v[216:219], v[24:27]
	v_mfma_f32_16x16x32_bf16 v[12:15], v[130:133], v[224:227], v[12:15]
	v_mfma_f32_16x16x32_bf16 v[8:11], v[142:145], v[224:227], v[8:11]
	v_mfma_f32_16x16x32_bf16 v[54:57], v[146:149], v[176:179], v[54:57]
	v_mfma_f32_16x16x32_bf16 v[50:53], v[168:171], v[176:179], v[50:53]
	v_mfma_f32_16x16x32_bf16 v[36:39], v[146:149], v[190:193], v[36:39]
	v_mfma_f32_16x16x32_bf16 v[32:35], v[168:171], v[190:193], v[32:35]
	v_mfma_f32_16x16x32_bf16 v[20:23], v[146:149], v[198:201], v[20:23]
	v_mfma_f32_16x16x32_bf16 v[16:19], v[168:171], v[198:201], v[16:19]
	v_mfma_f32_16x16x32_bf16 v[4:7], v[146:149], v[220:223], v[4:7]
	v_mfma_f32_16x16x32_bf16 v[0:3], v[168:171], v[220:223], v[0:3]
	v_mfma_f32_16x16x32_bf16 v[54:57], v[150:153], v[186:189], v[54:57]
	v_mfma_f32_16x16x32_bf16 v[50:53], v[172:175], v[186:189], v[50:53]
	v_mfma_f32_16x16x32_bf16 v[36:39], v[150:153], v[194:197], v[36:39]
	v_mfma_f32_16x16x32_bf16 v[32:35], v[172:175], v[194:197], v[32:35]
	v_mfma_f32_16x16x32_bf16 v[20:23], v[150:153], v[216:219], v[20:23]
	v_mfma_f32_16x16x32_bf16 v[16:19], v[172:175], v[216:219], v[16:19]
	v_mfma_f32_16x16x32_bf16 v[4:7], v[150:153], v[224:227], v[4:7]
	v_mfma_f32_16x16x32_bf16 v[0:3], v[172:175], v[224:227], v[0:3]
	s_setprio 0
	s_barrier
	s_add_i32 s6, 0, 0x18000
	v_add_u32_e32 v48, s6, v183
	s_add_i32 s26, 0, 0x1c000
	ds_read_b128 v[122:125], v48
	ds_read_b128 v[130:133], v48 offset:1024
	ds_read_b128 v[138:141], v48 offset:2048
	ds_read_b128 v[142:145], v48 offset:3072
	v_add_u32_e32 v48, s26, v183
	ds_read_b128 v[146:149], v48
	ds_read_b128 v[150:153], v48 offset:1024
	ds_read_b128 v[168:171], v48 offset:2048
	ds_read_b128 v[172:175], v48 offset:3072
	s_add_u32 s20, s60, 0x40000
	s_addc_u32 s21, s61, 0
	s_mov_b32 m0, s63
	v_lshl_add_u64 v[228:229], s[20:21], 0, v[156:157]
	ds_read_b128 v[176:179], v185 offset:32768
	ds_read_b128 v[186:189], v185 offset:33792
	ds_read_b128 v[190:193], v185 offset:34816
	ds_read_b128 v[194:197], v185 offset:35840
	ds_read_b128 v[198:201], v185 offset:36864
	ds_read_b128 v[216:219], v185 offset:37888
	ds_read_b128 v[220:223], v185 offset:38912
	ds_read_b128 v[224:227], v185 offset:39936
	global_load_lds_dwordx4 v[228:229], off
	v_lshl_add_u64 v[228:229], s[20:21], 0, v[160:161]
	s_mov_b32 m0, s64
	s_nop 0
	global_load_lds_dwordx4 v[228:229], off
	s_waitcnt vmcnt(8)
	s_waitcnt lgkmcnt(0)
	s_barrier
	s_setprio 1
	v_mfma_f32_16x16x32_bf16 v[134:137], v[122:125], v[176:179], v[134:137]
	v_mfma_f32_16x16x32_bf16 v[126:129], v[138:141], v[176:179], v[126:129]
	v_mfma_f32_16x16x32_bf16 v[110:113], v[122:125], v[190:193], v[110:113]
	v_mfma_f32_16x16x32_bf16 v[106:109], v[138:141], v[190:193], v[106:109]
	v_mfma_f32_16x16x32_bf16 v[94:97], v[122:125], v[198:201], v[94:97]
	v_mfma_f32_16x16x32_bf16 v[90:93], v[138:141], v[198:201], v[90:93]
	v_mfma_f32_16x16x32_bf16 v[78:81], v[122:125], v[220:223], v[78:81]
	v_mfma_f32_16x16x32_bf16 v[74:77], v[138:141], v[220:223], v[74:77]
	v_mfma_f32_16x16x32_bf16 v[134:137], v[130:133], v[186:189], v[134:137]
	v_mfma_f32_16x16x32_bf16 v[126:129], v[142:145], v[186:189], v[126:129]
	v_mfma_f32_16x16x32_bf16 v[110:113], v[130:133], v[194:197], v[110:113]
	v_mfma_f32_16x16x32_bf16 v[106:109], v[142:145], v[194:197], v[106:109]
	v_mfma_f32_16x16x32_bf16 v[94:97], v[130:133], v[216:219], v[94:97]
	v_mfma_f32_16x16x32_bf16 v[90:93], v[142:145], v[216:219], v[90:93]
	v_mfma_f32_16x16x32_bf16 v[78:81], v[130:133], v[224:227], v[78:81]
	v_mfma_f32_16x16x32_bf16 v[74:77], v[142:145], v[224:227], v[74:77]
	v_mfma_f32_16x16x32_bf16 v[118:121], v[146:149], v[176:179], v[118:121]
	v_mfma_f32_16x16x32_bf16 v[114:117], v[168:171], v[176:179], v[114:117]
	v_mfma_f32_16x16x32_bf16 v[102:105], v[146:149], v[190:193], v[102:105]
	v_mfma_f32_16x16x32_bf16 v[98:101], v[168:171], v[190:193], v[98:101]
	v_mfma_f32_16x16x32_bf16 v[86:89], v[146:149], v[198:201], v[86:89]
	v_mfma_f32_16x16x32_bf16 v[82:85], v[168:171], v[198:201], v[82:85]
	v_mfma_f32_16x16x32_bf16 v[70:73], v[146:149], v[220:223], v[70:73]
	v_mfma_f32_16x16x32_bf16 v[66:69], v[168:171], v[220:223], v[66:69]
	v_mfma_f32_16x16x32_bf16 v[118:121], v[150:153], v[186:189], v[118:121]
	v_mfma_f32_16x16x32_bf16 v[114:117], v[172:175], v[186:189], v[114:117]
	v_mfma_f32_16x16x32_bf16 v[102:105], v[150:153], v[194:197], v[102:105]
	v_mfma_f32_16x16x32_bf16 v[98:101], v[172:175], v[194:197], v[98:101]
	v_mfma_f32_16x16x32_bf16 v[86:89], v[150:153], v[216:219], v[86:89]
	v_mfma_f32_16x16x32_bf16 v[82:85], v[172:175], v[216:219], v[82:85]
	v_mfma_f32_16x16x32_bf16 v[70:73], v[150:153], v[224:227], v[70:73]
	v_mfma_f32_16x16x32_bf16 v[66:69], v[172:175], v[224:227], v[66:69]
	s_setprio 0
	s_barrier
	s_add_i32 s6, s6, s24
	v_lshl_add_u64 v[180:181], v[180:181], 0, s[30:31]
	s_mov_b32 m0, s6
	ds_read_b128 v[176:179], v185 offset:49152
	ds_read_b128 v[186:189], v185 offset:50176
	ds_read_b128 v[190:193], v185 offset:51200
	ds_read_b128 v[194:197], v185 offset:52224
	ds_read_b128 v[198:201], v185 offset:53248
	ds_read_b128 v[216:219], v185 offset:54272
	ds_read_b128 v[220:223], v185 offset:55296
	ds_read_b128 v[224:227], v185 offset:56320
	global_load_lds_dwordx4 v[180:181], off
	s_add_i32 m0, s6, 0x2000
	s_add_u32 s20, s58, 0x40080
	v_lshl_add_u64 v[180:181], v[202:203], 0, s[30:31]
	s_addc_u32 s21, s59, 0
	s_add_i32 s6, s26, s24
	global_load_lds_dwordx4 v[180:181], off
	v_lshl_add_u64 v[180:181], s[20:21], 0, v[158:159]
	s_mov_b32 m0, s6
	s_nop 0
	global_load_lds_dwordx4 v[180:181], off
	v_lshl_add_u64 v[180:181], s[20:21], 0, v[162:163]
	s_add_i32 m0, s6, 0x2000
	s_nop 0
	global_load_lds_dwordx4 v[180:181], off
	v_lshl_add_u64 v[180:181], v[212:213], 0, s[30:31]
	s_mov_b32 m0, s65
	s_nop 0
	global_load_lds_dwordx4 v[180:181], off
	v_lshl_add_u64 v[180:181], v[214:215], 0, s[30:31]
	s_mov_b32 m0, s66
	s_nop 0
	global_load_lds_dwordx4 v[180:181], off
	s_waitcnt vmcnt(8)
	s_waitcnt lgkmcnt(0)
	s_barrier
	s_setprio 1
	v_mfma_f32_16x16x32_bf16 v[62:65], v[122:125], v[176:179], v[62:65]
	v_mfma_f32_16x16x32_bf16 v[58:61], v[138:141], v[176:179], v[58:61]
	v_mfma_f32_16x16x32_bf16 v[44:47], v[122:125], v[190:193], v[44:47]
	v_mfma_f32_16x16x32_bf16 v[40:43], v[138:141], v[190:193], v[40:43]
	v_mfma_f32_16x16x32_bf16 v[28:31], v[122:125], v[198:201], v[28:31]
	v_mfma_f32_16x16x32_bf16 v[24:27], v[138:141], v[198:201], v[24:27]
	v_mfma_f32_16x16x32_bf16 v[12:15], v[122:125], v[220:223], v[12:15]
	v_mfma_f32_16x16x32_bf16 v[8:11], v[138:141], v[220:223], v[8:11]
	v_mfma_f32_16x16x32_bf16 v[62:65], v[130:133], v[186:189], v[62:65]
	v_mfma_f32_16x16x32_bf16 v[58:61], v[142:145], v[186:189], v[58:61]
	v_mfma_f32_16x16x32_bf16 v[44:47], v[130:133], v[194:197], v[44:47]
	v_mfma_f32_16x16x32_bf16 v[40:43], v[142:145], v[194:197], v[40:43]
	v_mfma_f32_16x16x32_bf16 v[28:31], v[130:133], v[216:219], v[28:31]
	v_mfma_f32_16x16x32_bf16 v[24:27], v[142:145], v[216:219], v[24:27]
	v_mfma_f32_16x16x32_bf16 v[12:15], v[130:133], v[224:227], v[12:15]
	v_mfma_f32_16x16x32_bf16 v[8:11], v[142:145], v[224:227], v[8:11]
	v_mfma_f32_16x16x32_bf16 v[54:57], v[146:149], v[176:179], v[54:57]
	v_mfma_f32_16x16x32_bf16 v[50:53], v[168:171], v[176:179], v[50:53]
	v_mfma_f32_16x16x32_bf16 v[36:39], v[146:149], v[190:193], v[36:39]
	v_mfma_f32_16x16x32_bf16 v[32:35], v[168:171], v[190:193], v[32:35]
	v_mfma_f32_16x16x32_bf16 v[20:23], v[146:149], v[198:201], v[20:23]
	v_mfma_f32_16x16x32_bf16 v[16:19], v[168:171], v[198:201], v[16:19]
	v_mfma_f32_16x16x32_bf16 v[4:7], v[146:149], v[220:223], v[4:7]
	v_mfma_f32_16x16x32_bf16 v[0:3], v[168:171], v[220:223], v[0:3]
	v_mfma_f32_16x16x32_bf16 v[54:57], v[150:153], v[186:189], v[54:57]
	v_mfma_f32_16x16x32_bf16 v[50:53], v[172:175], v[186:189], v[50:53]
	v_mfma_f32_16x16x32_bf16 v[36:39], v[150:153], v[194:197], v[36:39]
	v_mfma_f32_16x16x32_bf16 v[32:35], v[172:175], v[194:197], v[32:35]
	v_mfma_f32_16x16x32_bf16 v[20:23], v[150:153], v[216:219], v[20:23]
	v_mfma_f32_16x16x32_bf16 v[16:19], v[172:175], v[216:219], v[16:19]
	v_mfma_f32_16x16x32_bf16 v[4:7], v[150:153], v[224:227], v[4:7]
	v_mfma_f32_16x16x32_bf16 v[0:3], v[172:175], v[224:227], v[0:3]
	s_setprio 0
	s_barrier
	s_add_i32 s70, s70, 2
	s_add_u32 s56, s56, 0x100
	s_addc_u32 s57, s57, 0
	s_add_u32 s53, s53, 0x100
	s_addc_u32 s69, s69, 0
	s_cmp_gt_u32 s70, 13
	s_cbranch_scc0 .LBB0_1301
	s_and_b64 vcc, exec, s[40:41]
	s_cbranch_vccz .LBB0_1304
	s_barrier

.LBB0_1411:
	s_add_u32 s6, s52, 0xfffc0080
	s_addc_u32 s20, s53, -1
	s_add_i32 s21, 0, 0x10000
	s_cmp_eq_u32 s67, 12
	s_cselect_b32 s57, s33, s20
	s_cselect_b32 s56, s39, s6
	v_add_u32_e32 v48, s21, v173
	s_cselect_b32 s55, s43, s66
	s_cselect_b32 s54, s45, s65
	s_add_i32 s6, 0, 0x14000
	ds_read_b128 v[138:141], v48
	ds_read_b128 v[142:145], v48 offset:1024
	ds_read_b128 v[146:149], v48 offset:2048
	ds_read_b128 v[150:153], v48 offset:3072
	v_add_u32_e32 v48, s6, v173
	ds_read_b128 v[156:159], v48
	ds_read_b128 v[160:163], v48 offset:1024
	ds_read_b128 v[164:167], v48 offset:2048
	ds_read_b128 v[168:171], v48 offset:3072
	v_lshl_add_u64 v[202:203], s[52:53], 0, v[134:135]
	s_add_i32 m0, s59, 0xc000
	ds_read_b128 v[178:181], v176
	ds_read_b128 v[182:185], v176 offset:1024
	ds_read_b128 v[186:189], v176 offset:2048
	ds_read_b128 v[190:193], v176 offset:3072
	ds_read_b128 v[194:197], v176 offset:4096
	ds_read_b128 v[198:201], v176 offset:5120
	ds_read_b128 v[216:219], v176 offset:6144
	ds_read_b128 v[220:223], v176 offset:7168
	global_load_lds_dwordx4 v[202:203], off
	v_lshl_add_u64 v[202:203], s[52:53], 0, v[136:137]
	s_add_i32 m0, s59, 0xe000
	s_nop 0
	global_load_lds_dwordx4 v[202:203], off
	s_waitcnt vmcnt(8)
	s_waitcnt lgkmcnt(0)
	s_barrier
	s_setprio 1
	v_mfma_f32_16x16x32_bf16 v[126:129], v[138:141], v[178:181], v[126:129]
	v_mfma_f32_16x16x32_bf16 v[122:125], v[146:149], v[178:181], v[122:125]
	v_mfma_f32_16x16x32_bf16 v[110:113], v[138:141], v[186:189], v[110:113]
	v_mfma_f32_16x16x32_bf16 v[106:109], v[146:149], v[186:189], v[106:109]
	v_mfma_f32_16x16x32_bf16 v[94:97], v[138:141], v[194:197], v[94:97]
	v_mfma_f32_16x16x32_bf16 v[90:93], v[146:149], v[194:197], v[90:93]
	v_mfma_f32_16x16x32_bf16 v[78:81], v[138:141], v[216:219], v[78:81]
	v_mfma_f32_16x16x32_bf16 v[74:77], v[146:149], v[216:219], v[74:77]
	v_mfma_f32_16x16x32_bf16 v[126:129], v[142:145], v[182:185], v[126:129]
	v_mfma_f32_16x16x32_bf16 v[122:125], v[150:153], v[182:185], v[122:125]
	v_mfma_f32_16x16x32_bf16 v[110:113], v[142:145], v[190:193], v[110:113]
	v_mfma_f32_16x16x32_bf16 v[106:109], v[150:153], v[190:193], v[106:109]
	v_mfma_f32_16x16x32_bf16 v[94:97], v[142:145], v[198:201], v[94:97]
	v_mfma_f32_16x16x32_bf16 v[90:93], v[150:153], v[198:201], v[90:93]
	v_mfma_f32_16x16x32_bf16 v[78:81], v[142:145], v[220:223], v[78:81]
	v_mfma_f32_16x16x32_bf16 v[74:77], v[150:153], v[220:223], v[74:77]
	v_mfma_f32_16x16x32_bf16 v[118:121], v[156:159], v[178:181], v[118:121]
	v_mfma_f32_16x16x32_bf16 v[114:117], v[164:167], v[178:181], v[114:117]
	v_mfma_f32_16x16x32_bf16 v[102:105], v[156:159], v[186:189], v[102:105]
	v_mfma_f32_16x16x32_bf16 v[98:101], v[164:167], v[186:189], v[98:101]
	v_mfma_f32_16x16x32_bf16 v[86:89], v[156:159], v[194:197], v[86:89]
	v_mfma_f32_16x16x32_bf16 v[82:85], v[164:167], v[194:197], v[82:85]
	v_mfma_f32_16x16x32_bf16 v[70:73], v[156:159], v[216:219], v[70:73]
	v_mfma_f32_16x16x32_bf16 v[66:69], v[164:167], v[216:219], v[66:69]
	v_mfma_f32_16x16x32_bf16 v[118:121], v[160:163], v[182:185], v[118:121]
	v_mfma_f32_16x16x32_bf16 v[114:117], v[168:171], v[182:185], v[114:117]
	v_mfma_f32_16x16x32_bf16 v[102:105], v[160:163], v[190:193], v[102:105]
	v_mfma_f32_16x16x32_bf16 v[98:101], v[168:171], v[190:193], v[98:101]
	v_mfma_f32_16x16x32_bf16 v[86:89], v[160:163], v[198:201], v[86:89]
	v_mfma_f32_16x16x32_bf16 v[82:85], v[168:171], v[198:201], v[82:85]
	v_mfma_f32_16x16x32_bf16 v[70:73], v[160:163], v[220:223], v[70:73]
	v_mfma_f32_16x16x32_bf16 v[66:69], v[168:171], v[220:223], v[66:69]
	s_setprio 0
	s_barrier
	s_add_i32 s20, s21, s58
	v_lshl_add_u64 v[202:203], s[54:55], 0, v[132:133]
	s_mov_b32 m0, s20
	ds_read_b128 v[178:181], v176 offset:16384
	ds_read_b128 v[182:185], v176 offset:17408
	ds_read_b128 v[186:189], v176 offset:18432
	ds_read_b128 v[190:193], v176 offset:19456
	ds_read_b128 v[194:197], v176 offset:20480
	ds_read_b128 v[198:201], v176 offset:21504
	ds_read_b128 v[216:219], v176 offset:22528
	ds_read_b128 v[220:223], v176 offset:23552
	global_load_lds_dwordx4 v[202:203], off
	s_add_i32 m0, s20, 0x2000
	s_add_u32 s20, s54, 0x40000
	v_lshl_add_u64 v[212:213], s[54:55], 0, v[130:131]
	s_addc_u32 s21, s55, 0
	s_add_i32 s6, s6, s58
	global_load_lds_dwordx4 v[212:213], off
	v_lshl_add_u64 v[214:215], s[20:21], 0, v[132:133]
	s_mov_b32 m0, s6
	v_lshl_add_u64 v[224:225], s[56:57], 0, v[130:131]
	global_load_lds_dwordx4 v[214:215], off
	v_lshl_add_u64 v[214:215], s[20:21], 0, v[130:131]
	s_add_i32 m0, s6, 0x2000
	s_nop 0
	global_load_lds_dwordx4 v[214:215], off
	v_lshl_add_u64 v[214:215], s[56:57], 0, v[132:133]
	s_mov_b32 m0, s59
	s_nop 0
	global_load_lds_dwordx4 v[214:215], off
	s_mov_b32 m0, s60
	s_nop 0
	global_load_lds_dwordx4 v[224:225], off
	s_waitcnt vmcnt(8)
	s_waitcnt lgkmcnt(0)
	s_barrier
	s_setprio 1
	v_mfma_f32_16x16x32_bf16 v[62:65], v[138:141], v[178:181], v[62:65]
	v_mfma_f32_16x16x32_bf16 v[58:61], v[146:149], v[178:181], v[58:61]
	v_mfma_f32_16x16x32_bf16 v[44:47], v[138:141], v[186:189], v[44:47]
	v_mfma_f32_16x16x32_bf16 v[40:43], v[146:149], v[186:189], v[40:43]
	v_mfma_f32_16x16x32_bf16 v[28:31], v[138:141], v[194:197], v[28:31]
	v_mfma_f32_16x16x32_bf16 v[24:27], v[146:149], v[194:197], v[24:27]
	v_mfma_f32_16x16x32_bf16 v[12:15], v[138:141], v[216:219], v[12:15]
	v_mfma_f32_16x16x32_bf16 v[8:11], v[146:149], v[216:219], v[8:11]
	v_mfma_f32_16x16x32_bf16 v[62:65], v[142:145], v[182:185], v[62:65]
	v_mfma_f32_16x16x32_bf16 v[58:61], v[150:153], v[182:185], v[58:61]
	v_mfma_f32_16x16x32_bf16 v[44:47], v[142:145], v[190:193], v[44:47]
	v_mfma_f32_16x16x32_bf16 v[40:43], v[150:153], v[190:193], v[40:43]
	v_mfma_f32_16x16x32_bf16 v[28:31], v[142:145], v[198:201], v[28:31]
	v_mfma_f32_16x16x32_bf16 v[24:27], v[150:153], v[198:201], v[24:27]
	v_mfma_f32_16x16x32_bf16 v[12:15], v[142:145], v[220:223], v[12:15]
	v_mfma_f32_16x16x32_bf16 v[8:11], v[150:153], v[220:223], v[8:11]
	v_mfma_f32_16x16x32_bf16 v[54:57], v[156:159], v[178:181], v[54:57]
	v_mfma_f32_16x16x32_bf16 v[50:53], v[164:167], v[178:181], v[50:53]
	v_mfma_f32_16x16x32_bf16 v[36:39], v[156:159], v[186:189], v[36:39]
	v_mfma_f32_16x16x32_bf16 v[32:35], v[164:167], v[186:189], v[32:35]
	v_mfma_f32_16x16x32_bf16 v[20:23], v[156:159], v[194:197], v[20:23]
	v_mfma_f32_16x16x32_bf16 v[16:19], v[164:167], v[194:197], v[16:19]
	v_mfma_f32_16x16x32_bf16 v[4:7], v[156:159], v[216:219], v[4:7]
	v_mfma_f32_16x16x32_bf16 v[0:3], v[164:167], v[216:219], v[0:3]
	v_mfma_f32_16x16x32_bf16 v[54:57], v[160:163], v[182:185], v[54:57]
	v_mfma_f32_16x16x32_bf16 v[50:53], v[168:171], v[182:185], v[50:53]
	v_mfma_f32_16x16x32_bf16 v[36:39], v[160:163], v[190:193], v[36:39]
	v_mfma_f32_16x16x32_bf16 v[32:35], v[168:171], v[190:193], v[32:35]
	v_mfma_f32_16x16x32_bf16 v[20:23], v[160:163], v[198:201], v[20:23]
	v_mfma_f32_16x16x32_bf16 v[16:19], v[168:171], v[198:201], v[16:19]
	v_mfma_f32_16x16x32_bf16 v[4:7], v[160:163], v[220:223], v[4:7]
	v_mfma_f32_16x16x32_bf16 v[0:3], v[168:171], v[220:223], v[0:3]
	s_setprio 0
	s_barrier
	s_add_i32 s6, 0, 0x18000
	v_add_u32_e32 v48, s6, v173
	s_add_i32 s26, 0, 0x1c000
	ds_read_b128 v[138:141], v48
	ds_read_b128 v[142:145], v48 offset:1024
	ds_read_b128 v[146:149], v48 offset:2048
	ds_read_b128 v[150:153], v48 offset:3072
	v_add_u32_e32 v48, s26, v173
	ds_read_b128 v[156:159], v48
	ds_read_b128 v[160:163], v48 offset:1024
	ds_read_b128 v[164:167], v48 offset:2048
	ds_read_b128 v[168:171], v48 offset:3072
	s_add_u32 s20, s56, 0x40000
	s_addc_u32 s21, s57, 0
	s_mov_b32 m0, s61
	v_lshl_add_u64 v[226:227], s[20:21], 0, v[132:133]
	ds_read_b128 v[178:181], v176 offset:32768
	ds_read_b128 v[182:185], v176 offset:33792
	ds_read_b128 v[186:189], v176 offset:34816
	ds_read_b128 v[190:193], v176 offset:35840
	ds_read_b128 v[194:197], v176 offset:36864
	ds_read_b128 v[198:201], v176 offset:37888
	ds_read_b128 v[216:219], v176 offset:38912
	ds_read_b128 v[220:223], v176 offset:39936
	global_load_lds_dwordx4 v[226:227], off
	v_lshl_add_u64 v[226:227], s[20:21], 0, v[130:131]
	s_mov_b32 m0, s62
	s_nop 0
	global_load_lds_dwordx4 v[226:227], off
	s_waitcnt vmcnt(8)
	s_waitcnt lgkmcnt(0)
	s_barrier
	s_setprio 1
	v_mfma_f32_16x16x32_bf16 v[126:129], v[138:141], v[178:181], v[126:129]
	v_mfma_f32_16x16x32_bf16 v[122:125], v[146:149], v[178:181], v[122:125]
	v_mfma_f32_16x16x32_bf16 v[110:113], v[138:141], v[186:189], v[110:113]
	v_mfma_f32_16x16x32_bf16 v[106:109], v[146:149], v[186:189], v[106:109]
	v_mfma_f32_16x16x32_bf16 v[94:97], v[138:141], v[194:197], v[94:97]
	v_mfma_f32_16x16x32_bf16 v[90:93], v[146:149], v[194:197], v[90:93]
	v_mfma_f32_16x16x32_bf16 v[78:81], v[138:141], v[216:219], v[78:81]
	v_mfma_f32_16x16x32_bf16 v[74:77], v[146:149], v[216:219], v[74:77]
	v_mfma_f32_16x16x32_bf16 v[126:129], v[142:145], v[182:185], v[126:129]
	v_mfma_f32_16x16x32_bf16 v[122:125], v[150:153], v[182:185], v[122:125]
	v_mfma_f32_16x16x32_bf16 v[110:113], v[142:145], v[190:193], v[110:113]
	v_mfma_f32_16x16x32_bf16 v[106:109], v[150:153], v[190:193], v[106:109]
	v_mfma_f32_16x16x32_bf16 v[94:97], v[142:145], v[198:201], v[94:97]
	v_mfma_f32_16x16x32_bf16 v[90:93], v[150:153], v[198:201], v[90:93]
	v_mfma_f32_16x16x32_bf16 v[78:81], v[142:145], v[220:223], v[78:81]
	v_mfma_f32_16x16x32_bf16 v[74:77], v[150:153], v[220:223], v[74:77]
	v_mfma_f32_16x16x32_bf16 v[118:121], v[156:159], v[178:181], v[118:121]
	v_mfma_f32_16x16x32_bf16 v[114:117], v[164:167], v[178:181], v[114:117]
	v_mfma_f32_16x16x32_bf16 v[102:105], v[156:159], v[186:189], v[102:105]
	v_mfma_f32_16x16x32_bf16 v[98:101], v[164:167], v[186:189], v[98:101]
	v_mfma_f32_16x16x32_bf16 v[86:89], v[156:159], v[194:197], v[86:89]
	v_mfma_f32_16x16x32_bf16 v[82:85], v[164:167], v[194:197], v[82:85]
	v_mfma_f32_16x16x32_bf16 v[70:73], v[156:159], v[216:219], v[70:73]
	v_mfma_f32_16x16x32_bf16 v[66:69], v[164:167], v[216:219], v[66:69]
	v_mfma_f32_16x16x32_bf16 v[118:121], v[160:163], v[182:185], v[118:121]
	v_mfma_f32_16x16x32_bf16 v[114:117], v[168:171], v[182:185], v[114:117]
	v_mfma_f32_16x16x32_bf16 v[102:105], v[160:163], v[190:193], v[102:105]
	v_mfma_f32_16x16x32_bf16 v[98:101], v[168:171], v[190:193], v[98:101]
	v_mfma_f32_16x16x32_bf16 v[86:89], v[160:163], v[198:201], v[86:89]
	v_mfma_f32_16x16x32_bf16 v[82:85], v[168:171], v[198:201], v[82:85]
	v_mfma_f32_16x16x32_bf16 v[70:73], v[160:163], v[220:223], v[70:73]
	v_mfma_f32_16x16x32_bf16 v[66:69], v[168:171], v[220:223], v[66:69]
	s_setprio 0
	s_barrier
	s_add_i32 s6, s6, s58
	v_lshl_add_u64 v[202:203], v[202:203], 0, s[30:31]
	s_mov_b32 m0, s6
	ds_read_b128 v[178:181], v176 offset:49152
	ds_read_b128 v[182:185], v176 offset:50176
	ds_read_b128 v[186:189], v176 offset:51200
	ds_read_b128 v[190:193], v176 offset:52224
	ds_read_b128 v[194:197], v176 offset:53248
	ds_read_b128 v[198:201], v176 offset:54272
	ds_read_b128 v[216:219], v176 offset:55296
	ds_read_b128 v[220:223], v176 offset:56320
	global_load_lds_dwordx4 v[202:203], off
	s_add_i32 m0, s6, 0x2000
	s_add_u32 s20, s54, 0x40080
	v_lshl_add_u64 v[202:203], v[212:213], 0, s[30:31]
	s_addc_u32 s21, s55, 0
	s_add_i32 s6, s26, s58
	global_load_lds_dwordx4 v[202:203], off
	v_lshl_add_u64 v[202:203], s[20:21], 0, v[132:133]
	s_mov_b32 m0, s6
	s_nop 0
	global_load_lds_dwordx4 v[202:203], off
	v_lshl_add_u64 v[202:203], s[20:21], 0, v[130:131]
	s_add_i32 m0, s6, 0x2000
	s_nop 0
	global_load_lds_dwordx4 v[202:203], off
	v_lshl_add_u64 v[202:203], v[214:215], 0, s[30:31]
	s_mov_b32 m0, s24
	s_nop 0
	global_load_lds_dwordx4 v[202:203], off
	v_lshl_add_u64 v[202:203], v[224:225], 0, s[30:31]
	s_mov_b32 m0, s63
	s_nop 0
	global_load_lds_dwordx4 v[202:203], off
	s_waitcnt vmcnt(8)
	s_waitcnt lgkmcnt(0)
	s_barrier
	s_setprio 1
	v_mfma_f32_16x16x32_bf16 v[62:65], v[138:141], v[178:181], v[62:65]
	v_mfma_f32_16x16x32_bf16 v[58:61], v[146:149], v[178:181], v[58:61]
	v_mfma_f32_16x16x32_bf16 v[44:47], v[138:141], v[186:189], v[44:47]
	v_mfma_f32_16x16x32_bf16 v[40:43], v[146:149], v[186:189], v[40:43]
	v_mfma_f32_16x16x32_bf16 v[28:31], v[138:141], v[194:197], v[28:31]
	v_mfma_f32_16x16x32_bf16 v[24:27], v[146:149], v[194:197], v[24:27]
	v_mfma_f32_16x16x32_bf16 v[12:15], v[138:141], v[216:219], v[12:15]
	v_mfma_f32_16x16x32_bf16 v[8:11], v[146:149], v[216:219], v[8:11]
	v_mfma_f32_16x16x32_bf16 v[62:65], v[142:145], v[182:185], v[62:65]
	v_mfma_f32_16x16x32_bf16 v[58:61], v[150:153], v[182:185], v[58:61]
	v_mfma_f32_16x16x32_bf16 v[44:47], v[142:145], v[190:193], v[44:47]
	v_mfma_f32_16x16x32_bf16 v[40:43], v[150:153], v[190:193], v[40:43]
	v_mfma_f32_16x16x32_bf16 v[28:31], v[142:145], v[198:201], v[28:31]
	v_mfma_f32_16x16x32_bf16 v[24:27], v[150:153], v[198:201], v[24:27]
	v_mfma_f32_16x16x32_bf16 v[12:15], v[142:145], v[220:223], v[12:15]
	v_mfma_f32_16x16x32_bf16 v[8:11], v[150:153], v[220:223], v[8:11]
	v_mfma_f32_16x16x32_bf16 v[54:57], v[156:159], v[178:181], v[54:57]
	v_mfma_f32_16x16x32_bf16 v[50:53], v[164:167], v[178:181], v[50:53]
	v_mfma_f32_16x16x32_bf16 v[36:39], v[156:159], v[186:189], v[36:39]
	v_mfma_f32_16x16x32_bf16 v[32:35], v[164:167], v[186:189], v[32:35]
	v_mfma_f32_16x16x32_bf16 v[20:23], v[156:159], v[194:197], v[20:23]
	v_mfma_f32_16x16x32_bf16 v[16:19], v[164:167], v[194:197], v[16:19]
	v_mfma_f32_16x16x32_bf16 v[4:7], v[156:159], v[216:219], v[4:7]
	v_mfma_f32_16x16x32_bf16 v[0:3], v[164:167], v[216:219], v[0:3]
	v_mfma_f32_16x16x32_bf16 v[54:57], v[160:163], v[182:185], v[54:57]
	v_mfma_f32_16x16x32_bf16 v[50:53], v[168:171], v[182:185], v[50:53]
	v_mfma_f32_16x16x32_bf16 v[36:39], v[160:163], v[190:193], v[36:39]
	v_mfma_f32_16x16x32_bf16 v[32:35], v[168:171], v[190:193], v[32:35]
	v_mfma_f32_16x16x32_bf16 v[20:23], v[160:163], v[198:201], v[20:23]
	v_mfma_f32_16x16x32_bf16 v[16:19], v[168:171], v[198:201], v[16:19]
	v_mfma_f32_16x16x32_bf16 v[4:7], v[160:163], v[220:223], v[4:7]
	v_mfma_f32_16x16x32_bf16 v[0:3], v[168:171], v[220:223], v[0:3]
	s_setprio 0
	s_barrier
	s_add_i32 s67, s67, 2
	s_add_u32 s52, s52, 0x100
	s_addc_u32 s53, s53, 0
	s_add_u32 s65, s65, 0x100
	s_addc_u32 s66, s66, 0
	s_cmp_gt_u32 s67, 13
	s_cbranch_scc0 .LBB0_1411
	s_and_b64 vcc, exec, s[40:41]
	s_cbranch_vccz .LBB0_1414
	s_barrier

.LBB0_1978:
	s_add_u32 s50, s48, 0x100
	s_addc_u32 s51, s49, 0
	s_add_i32 s6, 0, 0x10000
	s_cmp_eq_u32 s68, 40
	s_cselect_b32 s55, s45, s51
	s_cselect_b32 s54, s44, s50
	v_add_u32_e32 v48, s6, v183
	s_cselect_b32 s53, s47, s67
	s_cselect_b32 s52, s46, s66
	s_add_i32 s26, 0, 0x14000
	ds_read_b128 v[122:125], v48
	ds_read_b128 v[130:133], v48 offset:1024
	ds_read_b128 v[138:141], v48 offset:2048
	ds_read_b128 v[142:145], v48 offset:3072
	v_add_u32_e32 v48, s26, v183
	ds_read_b128 v[146:149], v48
	ds_read_b128 v[150:153], v48 offset:1024
	ds_read_b128 v[168:171], v48 offset:2048
	ds_read_b128 v[172:175], v48 offset:3072
	v_lshl_add_u64 v[180:181], s[48:49], 0, v[164:165]
	s_add_i32 m0, s56, 0xc000
	ds_read_b128 v[176:179], v185
	ds_read_b128 v[186:189], v185 offset:1024
	ds_read_b128 v[190:193], v185 offset:2048
	ds_read_b128 v[194:197], v185 offset:3072
	ds_read_b128 v[198:201], v185 offset:4096
	ds_read_b128 v[216:219], v185 offset:5120
	ds_read_b128 v[220:223], v185 offset:6144
	ds_read_b128 v[224:227], v185 offset:7168
	global_load_lds_dwordx4 v[180:181], off
	v_lshl_add_u64 v[180:181], s[48:49], 0, v[166:167]
	s_add_i32 m0, s56, 0xe000
	s_nop 0
	global_load_lds_dwordx4 v[180:181], off
	s_waitcnt vmcnt(8)
	s_waitcnt lgkmcnt(0)
	s_barrier
	s_setprio 1
	v_mfma_f32_16x16x32_bf16 v[134:137], v[122:125], v[176:179], v[134:137]
	v_mfma_f32_16x16x32_bf16 v[126:129], v[138:141], v[176:179], v[126:129]
	v_mfma_f32_16x16x32_bf16 v[110:113], v[122:125], v[190:193], v[110:113]
	v_mfma_f32_16x16x32_bf16 v[106:109], v[138:141], v[190:193], v[106:109]
	v_mfma_f32_16x16x32_bf16 v[94:97], v[122:125], v[198:201], v[94:97]
	v_mfma_f32_16x16x32_bf16 v[90:93], v[138:141], v[198:201], v[90:93]
	v_mfma_f32_16x16x32_bf16 v[78:81], v[122:125], v[220:223], v[78:81]
	v_mfma_f32_16x16x32_bf16 v[74:77], v[138:141], v[220:223], v[74:77]
	v_mfma_f32_16x16x32_bf16 v[134:137], v[130:133], v[186:189], v[134:137]
	v_mfma_f32_16x16x32_bf16 v[126:129], v[142:145], v[186:189], v[126:129]
	v_mfma_f32_16x16x32_bf16 v[110:113], v[130:133], v[194:197], v[110:113]
	v_mfma_f32_16x16x32_bf16 v[106:109], v[142:145], v[194:197], v[106:109]
	v_mfma_f32_16x16x32_bf16 v[94:97], v[130:133], v[216:219], v[94:97]
	v_mfma_f32_16x16x32_bf16 v[90:93], v[142:145], v[216:219], v[90:93]
	v_mfma_f32_16x16x32_bf16 v[78:81], v[130:133], v[224:227], v[78:81]
	v_mfma_f32_16x16x32_bf16 v[74:77], v[142:145], v[224:227], v[74:77]
	v_mfma_f32_16x16x32_bf16 v[118:121], v[146:149], v[176:179], v[118:121]
	v_mfma_f32_16x16x32_bf16 v[114:117], v[168:171], v[176:179], v[114:117]
	v_mfma_f32_16x16x32_bf16 v[102:105], v[146:149], v[190:193], v[102:105]
	v_mfma_f32_16x16x32_bf16 v[98:101], v[168:171], v[190:193], v[98:101]
	v_mfma_f32_16x16x32_bf16 v[86:89], v[146:149], v[198:201], v[86:89]
	v_mfma_f32_16x16x32_bf16 v[82:85], v[168:171], v[198:201], v[82:85]
	v_mfma_f32_16x16x32_bf16 v[70:73], v[146:149], v[220:223], v[70:73]
	v_mfma_f32_16x16x32_bf16 v[66:69], v[168:171], v[220:223], v[66:69]
	v_mfma_f32_16x16x32_bf16 v[118:121], v[150:153], v[186:189], v[118:121]
	v_mfma_f32_16x16x32_bf16 v[114:117], v[172:175], v[186:189], v[114:117]
	v_mfma_f32_16x16x32_bf16 v[102:105], v[150:153], v[194:197], v[102:105]
	v_mfma_f32_16x16x32_bf16 v[98:101], v[172:175], v[194:197], v[98:101]
	v_mfma_f32_16x16x32_bf16 v[86:89], v[150:153], v[216:219], v[86:89]
	v_mfma_f32_16x16x32_bf16 v[82:85], v[172:175], v[216:219], v[82:85]
	v_mfma_f32_16x16x32_bf16 v[70:73], v[150:153], v[224:227], v[70:73]
	v_mfma_f32_16x16x32_bf16 v[66:69], v[172:175], v[224:227], v[66:69]
	s_setprio 0
	s_barrier
	s_add_i32 s6, s6, s24
	v_lshl_add_u64 v[180:181], s[52:53], 0, v[158:159]
	s_mov_b32 m0, s6
	ds_read_b128 v[176:179], v185 offset:16384
	ds_read_b128 v[186:189], v185 offset:17408
	ds_read_b128 v[190:193], v185 offset:18432
	ds_read_b128 v[194:197], v185 offset:19456
	ds_read_b128 v[198:201], v185 offset:20480
	ds_read_b128 v[216:219], v185 offset:21504
	ds_read_b128 v[220:223], v185 offset:22528
	ds_read_b128 v[224:227], v185 offset:23552
	global_load_lds_dwordx4 v[180:181], off
	s_add_i32 m0, s6, 0x2000
	s_add_u32 s20, s52, 0xb0000
	v_lshl_add_u64 v[202:203], s[52:53], 0, v[162:163]
	s_addc_u32 s21, s53, 0
	s_add_i32 s6, s26, s24
	global_load_lds_dwordx4 v[202:203], off
	v_lshl_add_u64 v[212:213], s[20:21], 0, v[158:159]
	s_mov_b32 m0, s6
	v_lshl_add_u64 v[214:215], s[54:55], 0, v[160:161]
	global_load_lds_dwordx4 v[212:213], off
	v_lshl_add_u64 v[212:213], s[20:21], 0, v[162:163]
	s_add_i32 m0, s6, 0x2000
	s_nop 0
	global_load_lds_dwordx4 v[212:213], off
	v_lshl_add_u64 v[212:213], s[54:55], 0, v[156:157]
	s_mov_b32 m0, s56
	s_nop 0
	global_load_lds_dwordx4 v[212:213], off
	s_mov_b32 m0, s57
	s_nop 0
	global_load_lds_dwordx4 v[214:215], off
	s_waitcnt vmcnt(8)
	s_waitcnt lgkmcnt(0)
	s_barrier
	s_setprio 1
	v_mfma_f32_16x16x32_bf16 v[62:65], v[122:125], v[176:179], v[62:65]
	v_mfma_f32_16x16x32_bf16 v[58:61], v[138:141], v[176:179], v[58:61]
	v_mfma_f32_16x16x32_bf16 v[44:47], v[122:125], v[190:193], v[44:47]
	v_mfma_f32_16x16x32_bf16 v[40:43], v[138:141], v[190:193], v[40:43]
	v_mfma_f32_16x16x32_bf16 v[28:31], v[122:125], v[198:201], v[28:31]
	v_mfma_f32_16x16x32_bf16 v[24:27], v[138:141], v[198:201], v[24:27]
	v_mfma_f32_16x16x32_bf16 v[12:15], v[122:125], v[220:223], v[12:15]
	v_mfma_f32_16x16x32_bf16 v[8:11], v[138:141], v[220:223], v[8:11]
	v_mfma_f32_16x16x32_bf16 v[62:65], v[130:133], v[186:189], v[62:65]
	v_mfma_f32_16x16x32_bf16 v[58:61], v[142:145], v[186:189], v[58:61]
	v_mfma_f32_16x16x32_bf16 v[44:47], v[130:133], v[194:197], v[44:47]
	v_mfma_f32_16x16x32_bf16 v[40:43], v[142:145], v[194:197], v[40:43]
	v_mfma_f32_16x16x32_bf16 v[28:31], v[130:133], v[216:219], v[28:31]
	v_mfma_f32_16x16x32_bf16 v[24:27], v[142:145], v[216:219], v[24:27]
	v_mfma_f32_16x16x32_bf16 v[12:15], v[130:133], v[224:227], v[12:15]
	v_mfma_f32_16x16x32_bf16 v[8:11], v[142:145], v[224:227], v[8:11]
	v_mfma_f32_16x16x32_bf16 v[54:57], v[146:149], v[176:179], v[54:57]
	v_mfma_f32_16x16x32_bf16 v[50:53], v[168:171], v[176:179], v[50:53]
	v_mfma_f32_16x16x32_bf16 v[36:39], v[146:149], v[190:193], v[36:39]
	v_mfma_f32_16x16x32_bf16 v[32:35], v[168:171], v[190:193], v[32:35]
	v_mfma_f32_16x16x32_bf16 v[20:23], v[146:149], v[198:201], v[20:23]
	v_mfma_f32_16x16x32_bf16 v[16:19], v[168:171], v[198:201], v[16:19]
	v_mfma_f32_16x16x32_bf16 v[4:7], v[146:149], v[220:223], v[4:7]
	v_mfma_f32_16x16x32_bf16 v[0:3], v[168:171], v[220:223], v[0:3]
	v_mfma_f32_16x16x32_bf16 v[54:57], v[150:153], v[186:189], v[54:57]
	v_mfma_f32_16x16x32_bf16 v[50:53], v[172:175], v[186:189], v[50:53]
	v_mfma_f32_16x16x32_bf16 v[36:39], v[150:153], v[194:197], v[36:39]
	v_mfma_f32_16x16x32_bf16 v[32:35], v[172:175], v[194:197], v[32:35]
	v_mfma_f32_16x16x32_bf16 v[20:23], v[150:153], v[216:219], v[20:23]
	v_mfma_f32_16x16x32_bf16 v[16:19], v[172:175], v[216:219], v[16:19]
	v_mfma_f32_16x16x32_bf16 v[4:7], v[150:153], v[224:227], v[4:7]
	v_mfma_f32_16x16x32_bf16 v[0:3], v[172:175], v[224:227], v[0:3]
	s_setprio 0
	s_barrier
	s_add_i32 s6, 0, 0x18000
	v_add_u32_e32 v48, s6, v183
	s_add_i32 s26, 0, 0x1c000
	ds_read_b128 v[122:125], v48
	ds_read_b128 v[130:133], v48 offset:1024
	ds_read_b128 v[138:141], v48 offset:2048
	ds_read_b128 v[142:145], v48 offset:3072
	v_add_u32_e32 v48, s26, v183
	ds_read_b128 v[146:149], v48
	ds_read_b128 v[150:153], v48 offset:1024
	ds_read_b128 v[168:171], v48 offset:2048
	ds_read_b128 v[172:175], v48 offset:3072
	s_add_u32 s20, s54, 0xb0000
	s_addc_u32 s21, s55, 0
	s_mov_b32 m0, s58
	v_lshl_add_u64 v[228:229], s[20:21], 0, v[156:157]
	ds_read_b128 v[176:179], v185 offset:32768
	ds_read_b128 v[186:189], v185 offset:33792
	ds_read_b128 v[190:193], v185 offset:34816
	ds_read_b128 v[194:197], v185 offset:35840
	ds_read_b128 v[198:201], v185 offset:36864
	ds_read_b128 v[216:219], v185 offset:37888
	ds_read_b128 v[220:223], v185 offset:38912
	ds_read_b128 v[224:227], v185 offset:39936
	global_load_lds_dwordx4 v[228:229], off
	v_lshl_add_u64 v[228:229], s[20:21], 0, v[160:161]
	s_mov_b32 m0, s59
	s_nop 0
	global_load_lds_dwordx4 v[228:229], off
	s_waitcnt vmcnt(8)
	s_waitcnt lgkmcnt(0)
	s_barrier
	s_setprio 1
	v_mfma_f32_16x16x32_bf16 v[134:137], v[122:125], v[176:179], v[134:137]
	v_mfma_f32_16x16x32_bf16 v[126:129], v[138:141], v[176:179], v[126:129]
	v_mfma_f32_16x16x32_bf16 v[110:113], v[122:125], v[190:193], v[110:113]
	v_mfma_f32_16x16x32_bf16 v[106:109], v[138:141], v[190:193], v[106:109]
	v_mfma_f32_16x16x32_bf16 v[94:97], v[122:125], v[198:201], v[94:97]
	v_mfma_f32_16x16x32_bf16 v[90:93], v[138:141], v[198:201], v[90:93]
	v_mfma_f32_16x16x32_bf16 v[78:81], v[122:125], v[220:223], v[78:81]
	v_mfma_f32_16x16x32_bf16 v[74:77], v[138:141], v[220:223], v[74:77]
	v_mfma_f32_16x16x32_bf16 v[134:137], v[130:133], v[186:189], v[134:137]
	v_mfma_f32_16x16x32_bf16 v[126:129], v[142:145], v[186:189], v[126:129]
	v_mfma_f32_16x16x32_bf16 v[110:113], v[130:133], v[194:197], v[110:113]
	v_mfma_f32_16x16x32_bf16 v[106:109], v[142:145], v[194:197], v[106:109]
	v_mfma_f32_16x16x32_bf16 v[94:97], v[130:133], v[216:219], v[94:97]
	v_mfma_f32_16x16x32_bf16 v[90:93], v[142:145], v[216:219], v[90:93]
	v_mfma_f32_16x16x32_bf16 v[78:81], v[130:133], v[224:227], v[78:81]
	v_mfma_f32_16x16x32_bf16 v[74:77], v[142:145], v[224:227], v[74:77]
	v_mfma_f32_16x16x32_bf16 v[118:121], v[146:149], v[176:179], v[118:121]
	v_mfma_f32_16x16x32_bf16 v[114:117], v[168:171], v[176:179], v[114:117]
	v_mfma_f32_16x16x32_bf16 v[102:105], v[146:149], v[190:193], v[102:105]
	v_mfma_f32_16x16x32_bf16 v[98:101], v[168:171], v[190:193], v[98:101]
	v_mfma_f32_16x16x32_bf16 v[86:89], v[146:149], v[198:201], v[86:89]
	v_mfma_f32_16x16x32_bf16 v[82:85], v[168:171], v[198:201], v[82:85]
	v_mfma_f32_16x16x32_bf16 v[70:73], v[146:149], v[220:223], v[70:73]
	v_mfma_f32_16x16x32_bf16 v[66:69], v[168:171], v[220:223], v[66:69]
	v_mfma_f32_16x16x32_bf16 v[118:121], v[150:153], v[186:189], v[118:121]
	v_mfma_f32_16x16x32_bf16 v[114:117], v[172:175], v[186:189], v[114:117]
	v_mfma_f32_16x16x32_bf16 v[102:105], v[150:153], v[194:197], v[102:105]
	v_mfma_f32_16x16x32_bf16 v[98:101], v[172:175], v[194:197], v[98:101]
	v_mfma_f32_16x16x32_bf16 v[86:89], v[150:153], v[216:219], v[86:89]
	v_mfma_f32_16x16x32_bf16 v[82:85], v[172:175], v[216:219], v[82:85]
	v_mfma_f32_16x16x32_bf16 v[70:73], v[150:153], v[224:227], v[70:73]
	v_mfma_f32_16x16x32_bf16 v[66:69], v[172:175], v[224:227], v[66:69]
	s_setprio 0
	s_barrier
	s_add_i32 s6, s6, s24
	v_lshl_add_u64 v[180:181], v[180:181], 0, s[30:31]
	s_mov_b32 m0, s6
	ds_read_b128 v[176:179], v185 offset:49152
	ds_read_b128 v[186:189], v185 offset:50176
	ds_read_b128 v[190:193], v185 offset:51200
	ds_read_b128 v[194:197], v185 offset:52224
	ds_read_b128 v[198:201], v185 offset:53248
	ds_read_b128 v[216:219], v185 offset:54272
	ds_read_b128 v[220:223], v185 offset:55296
	ds_read_b128 v[224:227], v185 offset:56320
	global_load_lds_dwordx4 v[180:181], off
	s_add_i32 m0, s6, 0x2000
	s_add_u32 s20, s52, 0xb0080
	v_lshl_add_u64 v[180:181], v[202:203], 0, s[30:31]
	s_addc_u32 s21, s53, 0
	s_add_i32 s6, s26, s24
	global_load_lds_dwordx4 v[180:181], off
	v_lshl_add_u64 v[180:181], s[20:21], 0, v[158:159]
	s_mov_b32 m0, s6
	s_nop 0
	global_load_lds_dwordx4 v[180:181], off
	v_lshl_add_u64 v[180:181], s[20:21], 0, v[162:163]
	s_add_i32 m0, s6, 0x2000
	s_nop 0
	global_load_lds_dwordx4 v[180:181], off
	v_lshl_add_u64 v[180:181], v[212:213], 0, s[30:31]
	s_mov_b32 m0, s60
	s_nop 0
	global_load_lds_dwordx4 v[180:181], off
	v_lshl_add_u64 v[180:181], v[214:215], 0, s[30:31]
	s_mov_b32 m0, s61
	s_nop 0
	global_load_lds_dwordx4 v[180:181], off
	s_waitcnt vmcnt(8)
	s_waitcnt lgkmcnt(0)
	s_barrier
	s_setprio 1
	v_mfma_f32_16x16x32_bf16 v[62:65], v[122:125], v[176:179], v[62:65]
	v_mfma_f32_16x16x32_bf16 v[58:61], v[138:141], v[176:179], v[58:61]
	v_mfma_f32_16x16x32_bf16 v[44:47], v[122:125], v[190:193], v[44:47]
	v_mfma_f32_16x16x32_bf16 v[40:43], v[138:141], v[190:193], v[40:43]
	v_mfma_f32_16x16x32_bf16 v[28:31], v[122:125], v[198:201], v[28:31]
	v_mfma_f32_16x16x32_bf16 v[24:27], v[138:141], v[198:201], v[24:27]
	v_mfma_f32_16x16x32_bf16 v[12:15], v[122:125], v[220:223], v[12:15]
	v_mfma_f32_16x16x32_bf16 v[8:11], v[138:141], v[220:223], v[8:11]
	v_mfma_f32_16x16x32_bf16 v[62:65], v[130:133], v[186:189], v[62:65]
	v_mfma_f32_16x16x32_bf16 v[58:61], v[142:145], v[186:189], v[58:61]
	v_mfma_f32_16x16x32_bf16 v[44:47], v[130:133], v[194:197], v[44:47]
	v_mfma_f32_16x16x32_bf16 v[40:43], v[142:145], v[194:197], v[40:43]
	v_mfma_f32_16x16x32_bf16 v[28:31], v[130:133], v[216:219], v[28:31]
	v_mfma_f32_16x16x32_bf16 v[24:27], v[142:145], v[216:219], v[24:27]
	v_mfma_f32_16x16x32_bf16 v[12:15], v[130:133], v[224:227], v[12:15]
	v_mfma_f32_16x16x32_bf16 v[8:11], v[142:145], v[224:227], v[8:11]
	v_mfma_f32_16x16x32_bf16 v[54:57], v[146:149], v[176:179], v[54:57]
	v_mfma_f32_16x16x32_bf16 v[50:53], v[168:171], v[176:179], v[50:53]
	v_mfma_f32_16x16x32_bf16 v[36:39], v[146:149], v[190:193], v[36:39]
	v_mfma_f32_16x16x32_bf16 v[32:35], v[168:171], v[190:193], v[32:35]
	v_mfma_f32_16x16x32_bf16 v[20:23], v[146:149], v[198:201], v[20:23]
	v_mfma_f32_16x16x32_bf16 v[16:19], v[168:171], v[198:201], v[16:19]
	v_mfma_f32_16x16x32_bf16 v[4:7], v[146:149], v[220:223], v[4:7]
	v_mfma_f32_16x16x32_bf16 v[0:3], v[168:171], v[220:223], v[0:3]
	v_mfma_f32_16x16x32_bf16 v[54:57], v[150:153], v[186:189], v[54:57]
	v_mfma_f32_16x16x32_bf16 v[50:53], v[172:175], v[186:189], v[50:53]
	v_mfma_f32_16x16x32_bf16 v[36:39], v[150:153], v[194:197], v[36:39]
	v_mfma_f32_16x16x32_bf16 v[32:35], v[172:175], v[194:197], v[32:35]
	v_mfma_f32_16x16x32_bf16 v[20:23], v[150:153], v[216:219], v[20:23]
	v_mfma_f32_16x16x32_bf16 v[16:19], v[172:175], v[216:219], v[16:19]
	v_mfma_f32_16x16x32_bf16 v[4:7], v[150:153], v[224:227], v[4:7]
	v_mfma_f32_16x16x32_bf16 v[0:3], v[172:175], v[224:227], v[0:3]
	s_setprio 0
	s_barrier
	s_add_i32 s68, s68, 2
	s_add_u32 s66, s66, 0x100
	s_addc_u32 s67, s67, 0
	s_cmp_gt_u32 s68, 41
	s_mov_b64 s[48:49], s[50:51]
	s_cbranch_scc0 .LBB0_1978
	s_and_b64 vcc, exec, s[42:43]
	s_cbranch_vccz .LBB0_1981
	s_barrier
